# non-temporal (nt) loads for the scan units' once-read decay/kt/kk/b rows (latent and context scans)
# speedup vs baseline: 1.0203x; 1.0061x over previous
.LBB0_952:
	s_and_b64 vcc, exec, s[0:1]
	s_cbranch_vccz .LBB0_960
	s_add_i32 s0, s24, 0xffa0
	s_and_b32 s1, s0, 0xffff
	s_mul_i32 s1, s1, 0xaaab
	s_lshr_b32 s22, s1, 19
	s_mul_i32 s1, s22, 12
	s_and_b32 s25, s24, 1
	s_sub_i32 s2, s0, s1
	s_mul_i32 s0, s25, 0x3c0000
	s_bfe_u32 s23, s2, 0xf0001
	s_lshl_b32 s26, s22, 8
	s_lshl_b32 s1, s0, 2
	s_add_u32 s4, s54, s1
	s_addc_u32 s5, s55, 0
	s_lshl_b32 s3, s0, 1
	s_add_u32 s6, s62, s3
	s_addc_u32 s7, s63, 0
	s_add_u32 s0, s64, s3
	s_addc_u32 s1, s65, 0
	s_lshl_b32 s2, s2, 5
	s_add_u32 s3, s70, s3
	s_addc_u32 s9, s71, 0
	s_and_b32 s10, s2, 0xffc0
	s_lshl_b32 s44, s10, 1
	s_add_u32 s8, s3, s44
	s_waitcnt vmcnt(6)
	v_mov_b32_e32 v24, v137
	s_addc_u32 s9, s9, 0
	s_cmp_eq_u32 s25, 0
	s_waitcnt vmcnt(1)
	v_ashrrev_i32_e32 v33, 4, v24
	v_lshlrev_b32_e32 v0, 2, v24
	v_and_b32_e32 v6, 60, v0
	v_sub_u32_e32 v0, 0xff, v33
	s_cselect_b64 s[2:3], -1, 0
	v_cndmask_b32_e64 v0, v0, v33, s[2:3]
	v_add_u32_e32 v7, s26, v0
	v_mul_lo_u32 v88, v7, s41
	v_lshlrev_b64 v[12:13], 1, v[88:89]
	v_lshl_add_u64 v[4:5], s[6:7], 0, v[12:13]
	v_lshl_add_u64 v[0:1], v[88:89], 2, s[4:5]
	v_lshl_add_u64 v[4:5], v[4:5], 0, s[44:45]
	v_lshlrev_b32_e32 v88, 1, v6
	v_lshl_add_u64 v[14:15], v[4:5], 0, v[88:89]
	v_mul_lo_u32 v4, v7, s48
	v_mov_b32_e32 v5, v89
	s_lshl_b32 s20, s10, 2
	s_mov_b32 s21, s45
	v_lshl_add_u64 v[4:5], v[4:5], 2, s[52:53]
	v_lshl_add_u64 v[0:1], v[0:1], 0, s[20:21]
	v_lshlrev_b32_e32 v20, 2, v6
	v_mov_b32_e32 v21, v89
	v_lshl_add_u64 v[4:5], v[4:5], 0, s[20:21]
	v_lshl_add_u64 v[0:1], v[0:1], 0, v[20:21]
	v_lshl_add_u64 v[8:9], v[4:5], 0, v[20:21]
	s_barrier
	global_load_dwordx4 v[0:3], v[0:1], off nt
	s_nop 0
	global_load_dwordx4 v[4:7], v[8:9], off
	s_nop 0
	global_load_dwordx4 v[8:11], v[8:9], off offset:3072
	s_nop 0
	global_load_dwordx2 v[30:31], v[14:15], off nt
	v_lshl_add_u64 v[14:15], s[74:75], 0, v[12:13]
	v_lshl_add_u64 v[14:15], v[14:15], 0, s[44:45]
	v_lshl_add_u64 v[12:13], s[0:1], 0, v[12:13]
	v_lshl_add_u64 v[14:15], v[14:15], 0, v[88:89]
	v_lshl_add_u64 v[12:13], v[12:13], 0, s[44:45]
	global_load_dwordx2 v[34:35], v[14:15], off nt
	v_lshl_add_u64 v[12:13], v[12:13], 0, v[88:89]
	global_load_dwordx2 v[38:39], v[12:13], off nt
	s_add_u32 s4, s4, s20
	s_addc_u32 s5, s5, 0
	v_lshl_add_u64 v[40:41], s[4:5], 0, v[20:21]
	s_add_u32 s4, s6, s44
	s_addc_u32 s5, s7, 0
	v_lshl_add_u64 v[42:43], s[4:5], 0, v[88:89]
	s_add_u32 s4, s74, s44
	s_addc_u32 s5, s75, 0
	s_add_u32 s0, s0, s44
	v_add_u32_e32 v32, 0, v20
	s_addc_u32 s1, s1, 0
	v_ashrrev_i32_e32 v116, 2, v24
	v_mad_u64_u32 v[22:23], s[10:11], v33, s49, v[32:33]
	v_lshl_add_u64 v[46:47], s[0:1], 0, v[88:89]
	s_add_u32 s0, s52, s20
	v_and_b32_e32 v28, -2, v116
	s_addc_u32 s1, s53, 0
	v_and_b32_e32 v118, 7, v24
	v_ashrrev_i32_e32 v29, 31, v28
	v_lshl_add_u64 v[48:49], s[0:1], 0, v[20:21]
	s_movk_i32 s0, 0xf7
	s_mov_b32 s21, 0
	s_mov_b32 s27, 16
	v_lshlrev_b32_e32 v117, 3, v118
	v_lshl_add_u64 v[36:37], v[28:29], 1, s[8:9]
	v_lshl_add_u64 v[44:45], s[4:5], 0, v[88:89]
	v_cmp_eq_u32_e64 s[4:5], 0, v118
	v_cmp_eq_u32_e64 s[6:7], 1, v118
	v_cmp_eq_u32_e64 s[8:9], 2, v118
	v_cmp_eq_u32_e64 s[10:11], 3, v118
	v_cmp_eq_u32_e64 s[12:13], 4, v118
	v_cmp_eq_u32_e64 s[14:15], 5, v118
	v_cmp_eq_u32_e64 s[16:17], 6, v118
	v_cmp_eq_u32_e64 s[18:19], 7, v118
	v_bitop3_b32 v29, v24, s0, 7 bitop3:0x6c
	v_sub_u32_e32 v119, 0xef, v33
	s_waitcnt vmcnt(5)
	ds_write_b128 v22, v[0:3]
	s_waitcnt vmcnt(4)
	ds_write_b128 v22, v[4:7] offset:1024
	s_waitcnt vmcnt(3)
	ds_write_b128 v22, v[8:11] offset:1280
	s_waitcnt vmcnt(2)
	v_lshlrev_b32_e32 v12, 16, v30
	v_and_b32_e32 v13, 0xffff0000, v30
	v_lshlrev_b32_e32 v14, 16, v31
	v_and_b32_e32 v15, 0xffff0000, v31
	ds_write_b128 v22, v[12:15] offset:256
	s_waitcnt vmcnt(1)
	v_lshlrev_b32_e32 v26, 16, v35
	v_lshlrev_b32_e32 v23, 16, v34
	v_and_b32_e32 v25, 0xffff0000, v34
	v_and_b32_e32 v27, 0xffff0000, v35
	s_waitcnt vmcnt(0)
	v_lshlrev_b32_e32 v16, 16, v38
	v_and_b32_e32 v17, 0xffff0000, v38
	v_lshlrev_b32_e32 v18, 16, v39
	v_and_b32_e32 v19, 0xffff0000, v39
	v_xor_b32_e32 v14, 0x80000000, v26
	v_xor_b32_e32 v13, 0x80000000, v25
	v_xor_b32_e32 v12, 0x80000000, v23
	v_xor_b32_e32 v15, 0x80000000, v27
	ds_write_b128 v22, v[16:19] offset:768
	ds_write_b128 v22, v[12:15] offset:512
	v_mov_b32_e32 v14, 0
	v_mov_b32_e32 v15, v14
	v_mov_b32_e32 v12, v14
	v_mov_b32_e32 v13, v14
	v_mov_b32_e32 v18, v14
	v_mov_b32_e32 v19, v14
	v_mov_b32_e32 v16, v14
	v_mov_b32_e32 v17, v14
	v_mov_b32_e32 v22, v14
	v_mov_b32_e32 v23, v14
	v_mov_b32_e32 v20, v14
	v_mov_b32_e32 v21, v14
	v_mov_b32_e32 v26, v14
	v_mov_b32_e32 v27, v14
	v_mov_b32_e32 v24, v14
	v_mov_b32_e32 v25, v14
	s_waitcnt lgkmcnt(0)
	s_barrier
	s_branch .LBB0_955

.LBB0_955:
	s_cmpk_lg_i32 s27, 0x100
	s_cselect_b64 s[0:1], -1, 0
	s_cmpk_eq_i32 s27, 0x100
	s_cbranch_scc1 .LBB0_957
	s_waitcnt vmcnt(7)
	v_add_u32_e32 v0, s27, v33
	v_cndmask_b32_e64 v0, v119, v0, s[2:3]
	s_waitcnt vmcnt(2)
	v_add_u32_e32 v8, s26, v0
	v_mul_lo_u32 v88, v8, s41
	v_lshlrev_b64 v[4:5], 1, v[88:89]
	v_lshl_add_u64 v[0:1], v[88:89], 2, v[40:41]
	v_lshl_add_u64 v[6:7], v[42:43], 0, v[4:5]
	v_mul_lo_u32 v88, v8, s48
	global_load_dwordx4 v[0:3], v[0:1], off nt
	s_nop 0
	global_load_dwordx2 v[30:31], v[6:7], off nt
	v_lshl_add_u64 v[6:7], v[44:45], 0, v[4:5]
	v_lshl_add_u64 v[4:5], v[46:47], 0, v[4:5]
	v_lshl_add_u64 v[8:9], v[88:89], 2, v[48:49]
	global_load_dwordx2 v[34:35], v[6:7], off nt
	global_load_dwordx2 v[38:39], v[4:5], off nt
	s_nop 0
	global_load_dwordx4 v[4:7], v[8:9], off
	s_nop 0
	global_load_dwordx4 v[8:11], v[8:9], off offset:3072

.LBB0_961:
	s_waitcnt vmcnt(0) lgkmcnt(0)
	v_readlane_b32 s0, v242, 42
	v_readlane_b32 s1, v242, 43
	v_readlane_b32 s4, v242, 3
	v_readlane_b32 s5, v242, 4
	s_lshr_b32 s6, s24, 2
	s_and_b32 s7, s24, 3
	s_cmp_gt_u32 s6, 11
	s_cselect_b32 s8, 1, 0
	s_mul_i32 s9, s8, 12
	s_sub_i32 s9, s6, s9
	s_sub_u32 s0, s0, 0x118
	s_subb_u32 s1, s1, 0
	s_load_dwordx2 s[2:3], s[0:1], 0x30
	s_lshr_b32 s10, s9, 1
	s_and_b32 s11, s9, 1
	s_lshl_b32 s29, s8, 1
	s_add_i32 s29, s29, 0
	s_lshl_b32 s29, s29, 1
	s_add_i32 s29, s29, s11
	s_mul_i32 s29, s29, 6
	s_add_i32 s29, s29, s10
	s_lshl_b32 s29, s29, 14
	v_and_b32_e32 v20, 15, v137
	v_lshrrev_b32_e32 v21, 4, v137
	v_lshlrev_b32_e32 v22, 4, v137
	s_lshl_b32 s38, s7, 12
	v_add_u32_e32 v22, s38, v22
	s_waitcnt lgkmcnt(0)
	s_add_u32 s2, s2, s29
	s_addc_u32 s3, s3, 0
	global_load_dwordx4 v[0:3], v22, s[2:3]
	s_mul_i32 s38, s11, 0xf00000
	s_mul_i32 s39, s11, 0x780000
	s_add_u32 s29, s38, 0x9278100
	s_add_u32 s12, s4, s29
	s_addc_u32 s13, s5, 0
	s_add_u32 s29, s39, 0xb078100
	s_add_u32 s14, s4, s29
	s_addc_u32 s15, s5, 0
	s_add_u32 s29, s39, 0xbf78100
	s_add_u32 s18, s4, s29
	s_addc_u32 s19, s5, 0
	s_add_u32 s29, s39, 0xddc8100
	s_add_u32 s22, s4, s29
	s_addc_u32 s23, s5, 0
	s_add_u32 s16, s4, 0xce78100
	s_addc_u32 s17, s5, 0
	s_add_u32 s20, s4, 0x5b78100
	s_addc_u32 s21, s5, 0
	s_lshl_b32 s38, s11, 1
	s_sub_i32 s38, 1, s38
	s_mul_i32 s25, s38, 24576
	s_mul_i32 s26, s38, 12288
	s_mul_i32 s27, s38, 0x16000
	s_lshl_b32 s39, s8, 10
	s_addk_i32 s39, 0x2000
	s_mul_i32 s44, s11, 1023
	s_add_i32 s39, s39, s44
	v_mul_i32_i24_e32 v23, s38, v21
	v_mul_i32_i24_e32 v24, s38, v20
	v_add_u32_e32 v23, s39, v23
	v_add_u32_e32 v24, s39, v24
	s_lshl_b32 s38, s10, 8
	s_lshl_b32 s39, s10, 7
	s_movk_i32 s44, 0x600
	v_lshlrev_b32_e32 v25, 4, v20
	v_mul_lo_u32 v174, v23, s44
	v_add3_u32 v174, v174, s38, v25
	s_movk_i32 s44, 0x300
	v_lshlrev_b32_e32 v26, 3, v20
	v_mul_lo_u32 v175, v23, s44
	v_add3_u32 v175, v175, s39, v26
	v_mul_lo_u32 v145, v24, s44
	s_lshl_b32 s44, s7, 5
	s_add_i32 s44, s44, s39
	v_lshlrev_b32_e32 v27, 1, v21
	v_add3_u32 v145, v145, s44, v27
	s_movk_i32 s44, 0x1600
	v_mul_lo_u32 v180, v23, s44
	v_lshlrev_b32_e32 v28, 2, v20
	s_lshl_b32 s44, s7, 6
	s_add_i32 s44, s44, s38
	s_addk_i32 s44, 0xc00
	v_add3_u32 v181, v180, s44, v28
	v_add3_u32 v180, v180, s38, v25
	v_mov_b32_e32 v88, v25
	v_lshlrev_b32_e32 v90, 4, v21
	v_mul_u32_u24_e32 v91, 0x600, v21
	v_add_u32_e32 v91, v91, v25
	v_and_b32_e32 v29, 1, v20
	v_and_b32_e32 v30, 2, v20
	v_cmp_ne_u32_e64 s[30:31], 0, v29
	v_cmp_ne_u32_e64 s[34:35], 0, v30
	v_and_b32_e32 v29, 3, v20
	v_cmp_eq_u32_e64 s[36:37], 3, v29
	s_mov_b32 s28, 0
	s_setprio 3
	global_load_dwordx4 v[104:107], v174, s[12:13] nt
	global_load_dwordx2 v[146:147], v175, s[14:15] nt
	global_load_dwordx2 v[148:149], v175, s[16:17] nt
	global_load_dwordx2 v[150:151], v175, s[18:19] nt
	global_load_dwordx4 v[108:111], v180, s[20:21]
	global_load_dword v170, v181, s[20:21]
	v_add_u32_e32 v174, s25, v174
	v_add_u32_e32 v175, s26, v175
	v_add_u32_e32 v180, s27, v180
	v_add_u32_e32 v181, s27, v181
	global_load_dwordx4 v[112:115], v174, s[12:13] nt
	global_load_dwordx2 v[152:153], v175, s[14:15] nt
	global_load_dwordx2 v[154:155], v175, s[16:17] nt
	global_load_dwordx2 v[156:157], v175, s[18:19] nt
	global_load_dwordx4 v[116:119], v180, s[20:21]
	global_load_dword v171, v181, s[20:21]
	v_add_u32_e32 v174, s25, v174
	v_add_u32_e32 v175, s26, v175
	v_add_u32_e32 v180, s27, v180
	v_add_u32_e32 v181, s27, v181
	global_load_dwordx4 v[120:123], v174, s[12:13] nt
	global_load_dwordx2 v[158:159], v175, s[14:15] nt
	global_load_dwordx2 v[160:161], v175, s[16:17] nt
	global_load_dwordx2 v[162:163], v175, s[18:19] nt
	global_load_dwordx4 v[124:127], v180, s[20:21]
	global_load_dword v172, v181, s[20:21]
	v_add_u32_e32 v174, s25, v174
	v_add_u32_e32 v175, s26, v175
	v_add_u32_e32 v180, s27, v180
	v_add_u32_e32 v181, s27, v181
	global_load_dwordx4 v[128:131], v174, s[12:13] nt
	global_load_dwordx2 v[164:165], v175, s[14:15] nt
	global_load_dwordx2 v[166:167], v175, s[16:17] nt
	global_load_dwordx2 v[168:169], v175, s[18:19] nt
	global_load_dwordx4 v[132:135], v180, s[20:21]
	global_load_dword v173, v181, s[20:21]
	v_add_u32_e32 v174, s25, v174
	v_add_u32_e32 v175, s26, v175
	v_add_u32_e32 v180, s27, v180
	v_add_u32_e32 v181, s27, v181
	s_waitcnt vmcnt(18)
	ds_write_b128 v91, v[104:107] offset:0
	ds_write_b128 v91, v[108:111] offset:1024
	ds_write_b32 v91, v170 offset:1280
	v_lshlrev_b32_e32 v176, 16, v146
	v_and_b32_e32 v177, 0xffff0000, v146
	v_lshlrev_b32_e32 v178, 16, v147
	v_and_b32_e32 v179, 0xffff0000, v147
	ds_write_b128 v91, v[176:179] offset:256
	v_lshlrev_b32_e32 v176, 16, v148
	v_and_b32_e32 v177, 0xffff0000, v148
	v_lshlrev_b32_e32 v178, 16, v149
	v_and_b32_e32 v179, 0xffff0000, v149
	ds_write_b128 v91, v[176:179] offset:512
	v_lshlrev_b32_e32 v176, 16, v150
	v_and_b32_e32 v177, 0xffff0000, v150
	v_lshlrev_b32_e32 v178, 16, v151
	v_and_b32_e32 v179, 0xffff0000, v151
	ds_write_b128 v91, v[176:179] offset:768
	s_waitcnt lgkmcnt(0)
	s_barrier
	ds_read_b128 v[28:31], v88 offset:512
	ds_read_b128 v[24:27], v88 offset:256
	ds_read_b128 v[20:23], v88 offset:0
	ds_read_b128 v[32:35], v88 offset:768
	ds_read_b128 v[36:39], v88 offset:1024
	ds_read2st64_b32 v[16:17], v90 offset0:5 offset1:11
	ds_read_b128 v[48:51], v88 offset:2048
	ds_read_b128 v[44:47], v88 offset:1792
	ds_read_b128 v[40:43], v88 offset:1536
	ds_read_b128 v[52:55], v88 offset:2304
	ds_read_b128 v[56:59], v88 offset:2560
.Lls0_loop:
	s_waitcnt lgkmcnt(5)
	v_pk_mul_f32 v[4:5], v[0:1], v[28:29] neg_lo:[0,1] neg_hi:[0,1]
	ds_read_b128 v[68:71], v88 offset:3584
	v_pk_fma_f32 v[4:5], v[2:3], v[30:31], v[4:5] neg_lo:[0,1,0] neg_hi:[0,1,0]
	ds_read_b128 v[64:67], v88 offset:3328
	v_pk_mul_f32 v[8:9], v[24:25], v[16:17] op_sel_hi:[1,0]
	v_add_f32_e32 v4, v4, v5
	ds_read_b128 v[60:63], v88 offset:3072
	v_pk_mul_f32 v[10:11], v[26:27], v[16:17] op_sel_hi:[1,0]
	v_add_f32_dpp v4, v4, v4 quad_perm:[1,0,3,2] row_mask:0xf bank_mask:0xf bound_ctrl:1
	ds_read_b128 v[72:75], v88 offset:3840
	v_pk_fma_f32 v[8:9], v[0:1], v[20:21], v[8:9]
	v_add_f32_dpp v4, v4, v4 quad_perm:[2,3,0,1] row_mask:0xf bank_mask:0xf bound_ctrl:1
	v_pk_fma_f32 v[10:11], v[2:3], v[22:23], v[10:11]
	v_add_f32_dpp v198, v198, v198 row_ror:8 row_mask:0xf bank_mask:0x3 bound_ctrl:1
	v_add_f32_dpp v4, v4, v4 row_ror:4 row_mask:0xf bank_mask:0xf bound_ctrl:1
	ds_read_b128 v[76:79], v88 offset:4096
	v_add_f32_dpp v198, v206, v206 row_ror:8 row_mask:0xf bank_mask:0xc bound_ctrl:1
	v_add_f32_dpp v4, v4, v4 row_ror:8 row_mask:0xf bank_mask:0xf bound_ctrl:1
	v_pk_fma_f32 v[0:1], v[4:5], v[32:33], v[8:9] op_sel_hi:[0,1,1]
	v_pk_fma_f32 v[2:3], v[4:5], v[34:35], v[10:11] op_sel_hi:[0,1,1]
	v_pk_mul_f32 v[6:7], v[0:1], v[36:37]
	v_pk_fma_f32 v[6:7], v[2:3], v[38:39], v[6:7]
	v_add_f32_e32 v182, v6, v7
	ds_read2st64_b32 v[18:19], v90 offset0:17 offset1:23
	s_cmp_lt_u32 s28, 15
	s_cbranch_scc0 .Lls0_skip0
	global_load_dwordx4 v[104:107], v174, s[12:13] nt
	global_load_dwordx2 v[146:147], v175, s[14:15] nt
	global_load_dwordx2 v[148:149], v175, s[16:17] nt
	global_load_dwordx2 v[150:151], v175, s[18:19] nt
	global_load_dwordx4 v[108:111], v180, s[20:21]
	global_load_dword v170, v181, s[20:21]
	v_add_u32_e32 v174, s25, v174
	v_add_u32_e32 v175, s26, v175
	v_add_u32_e32 v180, s27, v180
	v_add_u32_e32 v181, s27, v181

.Lls0_noy:
	v_and_b32_e32 v177, 0xffff0000, v154
	v_lshlrev_b32_e32 v178, 16, v155
	s_waitcnt lgkmcnt(6)
	v_pk_mul_f32 v[4:5], v[0:1], v[68:69] neg_lo:[0,1] neg_hi:[0,1]
	ds_read_b128 v[28:31], v88 offset:18944
	v_pk_fma_f32 v[4:5], v[2:3], v[70:71], v[4:5] neg_lo:[0,1,0] neg_hi:[0,1,0]
	ds_read_b128 v[24:27], v88 offset:18688
	v_pk_mul_f32 v[8:9], v[64:65], v[18:19] op_sel_hi:[1,0]
	v_add_f32_e32 v4, v4, v5
	ds_read_b128 v[20:23], v88 offset:18432
	v_pk_mul_f32 v[10:11], v[66:67], v[18:19] op_sel_hi:[1,0]
	v_add_f32_dpp v4, v4, v4 quad_perm:[1,0,3,2] row_mask:0xf bank_mask:0xf bound_ctrl:1
	ds_read_b128 v[32:35], v88 offset:19200
	v_pk_fma_f32 v[8:9], v[0:1], v[60:61], v[8:9]
	v_add_f32_dpp v4, v4, v4 quad_perm:[2,3,0,1] row_mask:0xf bank_mask:0xf bound_ctrl:1
	v_pk_fma_f32 v[10:11], v[2:3], v[62:63], v[10:11]
	s_nop 0
	v_add_f32_dpp v4, v4, v4 row_ror:4 row_mask:0xf bank_mask:0xf bound_ctrl:1
	ds_read_b128 v[36:39], v88 offset:19456
	s_nop 0
	v_add_f32_dpp v4, v4, v4 row_ror:8 row_mask:0xf bank_mask:0xf bound_ctrl:1
	v_pk_fma_f32 v[0:1], v[4:5], v[72:73], v[8:9] op_sel_hi:[0,1,1]
	v_pk_fma_f32 v[2:3], v[4:5], v[74:75], v[10:11] op_sel_hi:[0,1,1]
	v_pk_mul_f32 v[6:7], v[0:1], v[76:77]
	v_pk_fma_f32 v[6:7], v[2:3], v[78:79], v[6:7]
	v_add_f32_e32 v192, v6, v7
	ds_read2st64_b32 v[16:17], v90 offset0:77 offset1:83
	v_and_b32_e32 v179, 0xffff0000, v155
	ds_write_b128 v91, v[176:179] offset:25088
	s_waitcnt lgkmcnt(7)
	v_pk_mul_f32 v[4:5], v[0:1], v[92:93] neg_lo:[0,1] neg_hi:[0,1]
	ds_read_b128 v[48:51], v88 offset:20480
	v_pk_fma_f32 v[4:5], v[2:3], v[94:95], v[4:5] neg_lo:[0,1,0] neg_hi:[0,1,0]
	ds_read_b128 v[44:47], v88 offset:20224
	v_pk_mul_f32 v[8:9], v[84:85], v[18:19] op_sel:[0,1] op_sel_hi:[1,1]
	v_add_f32_e32 v4, v4, v5
	ds_read_b128 v[40:43], v88 offset:19968
	v_pk_mul_f32 v[10:11], v[86:87], v[18:19] op_sel:[0,1] op_sel_hi:[1,1]
	v_add_f32_dpp v4, v4, v4 quad_perm:[1,0,3,2] row_mask:0xf bank_mask:0xf bound_ctrl:1
	ds_read_b128 v[52:55], v88 offset:20736
	v_pk_fma_f32 v[8:9], v[0:1], v[80:81], v[8:9]
	v_add_f32_dpp v4, v4, v4 quad_perm:[2,3,0,1] row_mask:0xf bank_mask:0xf bound_ctrl:1
	v_pk_fma_f32 v[10:11], v[2:3], v[82:83], v[10:11]
	s_nop 0
	v_add_f32_dpp v4, v4, v4 row_ror:4 row_mask:0xf bank_mask:0xf bound_ctrl:1
	ds_read_b128 v[56:59], v88 offset:20992
	s_nop 0
	v_add_f32_dpp v4, v4, v4 row_ror:8 row_mask:0xf bank_mask:0xf bound_ctrl:1
	v_pk_fma_f32 v[0:1], v[4:5], v[96:97], v[8:9] op_sel_hi:[0,1,1]
	v_pk_fma_f32 v[2:3], v[4:5], v[98:99], v[10:11] op_sel_hi:[0,1,1]
	v_pk_mul_f32 v[6:7], v[0:1], v[100:101]
	v_pk_fma_f32 v[6:7], v[2:3], v[102:103], v[6:7]
	v_add_f32_e32 v193, v6, v7
	v_lshlrev_b32_e32 v176, 16, v156
	v_and_b32_e32 v177, 0xffff0000, v156
	s_waitcnt lgkmcnt(6)
	v_pk_mul_f32 v[4:5], v[0:1], v[28:29] neg_lo:[0,1] neg_hi:[0,1]
	ds_read_b128 v[68:71], v88 offset:22016
	v_pk_fma_f32 v[4:5], v[2:3], v[30:31], v[4:5] neg_lo:[0,1,0] neg_hi:[0,1,0]
	ds_read_b128 v[64:67], v88 offset:21760
	v_pk_mul_f32 v[8:9], v[24:25], v[16:17] op_sel_hi:[1,0]
	v_add_f32_e32 v4, v4, v5
	ds_read_b128 v[60:63], v88 offset:21504
	v_pk_mul_f32 v[10:11], v[26:27], v[16:17] op_sel_hi:[1,0]
	v_add_f32_dpp v4, v4, v4 quad_perm:[1,0,3,2] row_mask:0xf bank_mask:0xf bound_ctrl:1
	ds_read_b128 v[72:75], v88 offset:22272
	v_pk_fma_f32 v[8:9], v[0:1], v[20:21], v[8:9]
	v_add_f32_dpp v4, v4, v4 quad_perm:[2,3,0,1] row_mask:0xf bank_mask:0xf bound_ctrl:1
	v_pk_fma_f32 v[10:11], v[2:3], v[22:23], v[10:11]
	s_nop 0
	v_add_f32_dpp v4, v4, v4 row_ror:4 row_mask:0xf bank_mask:0xf bound_ctrl:1
	ds_read_b128 v[76:79], v88 offset:22528
	s_nop 0
	v_add_f32_dpp v4, v4, v4 row_ror:8 row_mask:0xf bank_mask:0xf bound_ctrl:1
	v_pk_fma_f32 v[0:1], v[4:5], v[32:33], v[8:9] op_sel_hi:[0,1,1]
	v_pk_fma_f32 v[2:3], v[4:5], v[34:35], v[10:11] op_sel_hi:[0,1,1]
	v_pk_mul_f32 v[6:7], v[0:1], v[36:37]
	v_pk_fma_f32 v[6:7], v[2:3], v[38:39], v[6:7]
	v_add_f32_e32 v194, v6, v7
	ds_read2st64_b32 v[18:19], v90 offset0:89 offset1:95
	v_lshlrev_b32_e32 v178, 16, v157
	v_and_b32_e32 v179, 0xffff0000, v157
	ds_write_b128 v91, v[176:179] offset:25344
	s_waitcnt lgkmcnt(7)
	v_pk_mul_f32 v[4:5], v[0:1], v[48:49] neg_lo:[0,1] neg_hi:[0,1]
	ds_read_b128 v[92:95], v88 offset:23552
	v_pk_fma_f32 v[4:5], v[2:3], v[50:51], v[4:5] neg_lo:[0,1,0] neg_hi:[0,1,0]
	ds_read_b128 v[84:87], v88 offset:23296
	v_pk_mul_f32 v[8:9], v[44:45], v[16:17] op_sel:[0,1] op_sel_hi:[1,1]
	v_add_f32_e32 v4, v4, v5
	ds_read_b128 v[80:83], v88 offset:23040
	v_pk_mul_f32 v[10:11], v[46:47], v[16:17] op_sel:[0,1] op_sel_hi:[1,1]
	v_add_f32_dpp v4, v4, v4 quad_perm:[1,0,3,2] row_mask:0xf bank_mask:0xf bound_ctrl:1
	ds_read_b128 v[96:99], v88 offset:23808
	v_pk_fma_f32 v[8:9], v[0:1], v[40:41], v[8:9]
	v_add_f32_dpp v4, v4, v4 quad_perm:[2,3,0,1] row_mask:0xf bank_mask:0xf bound_ctrl:1
	v_pk_fma_f32 v[10:11], v[2:3], v[42:43], v[10:11]
	s_nop 0
	v_add_f32_dpp v4, v4, v4 row_ror:4 row_mask:0xf bank_mask:0xf bound_ctrl:1
	ds_read_b128 v[100:103], v88 offset:24064
	s_nop 0
	v_add_f32_dpp v4, v4, v4 row_ror:8 row_mask:0xf bank_mask:0xf bound_ctrl:1
	v_pk_fma_f32 v[0:1], v[4:5], v[52:53], v[8:9] op_sel_hi:[0,1,1]
	v_pk_fma_f32 v[2:3], v[4:5], v[54:55], v[10:11] op_sel_hi:[0,1,1]
	v_pk_mul_f32 v[6:7], v[0:1], v[56:57]
	v_pk_fma_f32 v[6:7], v[2:3], v[58:59], v[6:7]
	v_add_f32_e32 v195, v6, v7
	s_waitcnt lgkmcnt(0)
	s_barrier
	v_pk_mul_f32 v[4:5], v[0:1], v[68:69] neg_lo:[0,1] neg_hi:[0,1]
	ds_read_b128 v[28:31], v88 offset:25088
	v_pk_fma_f32 v[4:5], v[2:3], v[70:71], v[4:5] neg_lo:[0,1,0] neg_hi:[0,1,0]
	ds_read_b128 v[24:27], v88 offset:24832
	v_pk_mul_f32 v[8:9], v[64:65], v[18:19] op_sel_hi:[1,0]
	v_add_f32_e32 v4, v4, v5
	ds_read_b128 v[20:23], v88 offset:24576
	v_pk_mul_f32 v[10:11], v[66:67], v[18:19] op_sel_hi:[1,0]
	v_add_f32_dpp v4, v4, v4 quad_perm:[1,0,3,2] row_mask:0xf bank_mask:0xf bound_ctrl:1
	ds_read_b128 v[32:35], v88 offset:25344
	v_pk_fma_f32 v[8:9], v[0:1], v[60:61], v[8:9]
	v_add_f32_dpp v4, v4, v4 quad_perm:[2,3,0,1] row_mask:0xf bank_mask:0xf bound_ctrl:1
	v_pk_fma_f32 v[10:11], v[2:3], v[62:63], v[10:11]
	s_nop 0
	v_add_f32_dpp v4, v4, v4 row_ror:4 row_mask:0xf bank_mask:0xf bound_ctrl:1
	ds_read_b128 v[36:39], v88 offset:25600
	s_nop 0
	v_add_f32_dpp v4, v4, v4 row_ror:8 row_mask:0xf bank_mask:0xf bound_ctrl:1
	v_pk_fma_f32 v[0:1], v[4:5], v[72:73], v[8:9] op_sel_hi:[0,1,1]
	v_pk_fma_f32 v[2:3], v[4:5], v[74:75], v[10:11] op_sel_hi:[0,1,1]
	v_pk_mul_f32 v[6:7], v[0:1], v[76:77]
	v_pk_fma_f32 v[6:7], v[2:3], v[78:79], v[6:7]
	v_add_f32_e32 v196, v6, v7
	ds_read2st64_b32 v[16:17], v90 offset0:101 offset1:107
	s_waitcnt lgkmcnt(6)
	v_pk_mul_f32 v[4:5], v[0:1], v[92:93] neg_lo:[0,1] neg_hi:[0,1]
	ds_read_b128 v[48:51], v88 offset:26624
	v_pk_fma_f32 v[4:5], v[2:3], v[94:95], v[4:5] neg_lo:[0,1,0] neg_hi:[0,1,0]
	ds_read_b128 v[44:47], v88 offset:26368
	v_pk_mul_f32 v[8:9], v[84:85], v[18:19] op_sel:[0,1] op_sel_hi:[1,1]
	v_add_f32_e32 v4, v4, v5
	ds_read_b128 v[40:43], v88 offset:26112
	v_pk_mul_f32 v[10:11], v[86:87], v[18:19] op_sel:[0,1] op_sel_hi:[1,1]
	v_add_f32_dpp v4, v4, v4 quad_perm:[1,0,3,2] row_mask:0xf bank_mask:0xf bound_ctrl:1
	ds_read_b128 v[52:55], v88 offset:26880
	v_pk_fma_f32 v[8:9], v[0:1], v[80:81], v[8:9]
	v_add_f32_dpp v4, v4, v4 quad_perm:[2,3,0,1] row_mask:0xf bank_mask:0xf bound_ctrl:1
	v_pk_fma_f32 v[10:11], v[2:3], v[82:83], v[10:11]
	s_nop 0
	v_add_f32_dpp v4, v4, v4 row_ror:4 row_mask:0xf bank_mask:0xf bound_ctrl:1
	ds_read_b128 v[56:59], v88 offset:27136
	s_nop 0
	v_add_f32_dpp v4, v4, v4 row_ror:8 row_mask:0xf bank_mask:0xf bound_ctrl:1
	v_pk_fma_f32 v[0:1], v[4:5], v[96:97], v[8:9] op_sel_hi:[0,1,1]
	v_pk_fma_f32 v[2:3], v[4:5], v[98:99], v[10:11] op_sel_hi:[0,1,1]
	v_pk_mul_f32 v[6:7], v[0:1], v[100:101]
	v_pk_fma_f32 v[6:7], v[2:3], v[102:103], v[6:7]
	v_add_f32_e32 v197, v6, v7
	s_waitcnt lgkmcnt(5)
	v_pk_mul_f32 v[4:5], v[0:1], v[28:29] neg_lo:[0,1] neg_hi:[0,1]
	ds_read_b128 v[68:71], v88 offset:28160
	v_pk_fma_f32 v[4:5], v[2:3], v[30:31], v[4:5] neg_lo:[0,1,0] neg_hi:[0,1,0]
	ds_read_b128 v[64:67], v88 offset:27904
	v_pk_mul_f32 v[8:9], v[24:25], v[16:17] op_sel_hi:[1,0]
	v_add_f32_e32 v4, v4, v5
	ds_read_b128 v[60:63], v88 offset:27648
	v_pk_mul_f32 v[10:11], v[26:27], v[16:17] op_sel_hi:[1,0]
	v_add_f32_dpp v4, v4, v4 quad_perm:[1,0,3,2] row_mask:0xf bank_mask:0xf bound_ctrl:1
	ds_read_b128 v[72:75], v88 offset:28416
	v_pk_fma_f32 v[8:9], v[0:1], v[20:21], v[8:9]
	v_add_f32_dpp v4, v4, v4 quad_perm:[2,3,0,1] row_mask:0xf bank_mask:0xf bound_ctrl:1
	v_pk_fma_f32 v[10:11], v[2:3], v[22:23], v[10:11]
	v_add_f32_dpp v182, v182, v182 row_ror:8 row_mask:0xf bank_mask:0x3 bound_ctrl:1
	v_add_f32_dpp v4, v4, v4 row_ror:4 row_mask:0xf bank_mask:0xf bound_ctrl:1
	ds_read_b128 v[76:79], v88 offset:28672
	v_add_f32_dpp v182, v190, v190 row_ror:8 row_mask:0xf bank_mask:0xc bound_ctrl:1
	v_add_f32_dpp v4, v4, v4 row_ror:8 row_mask:0xf bank_mask:0xf bound_ctrl:1
	v_pk_fma_f32 v[0:1], v[4:5], v[32:33], v[8:9] op_sel_hi:[0,1,1]
	v_pk_fma_f32 v[2:3], v[4:5], v[34:35], v[10:11] op_sel_hi:[0,1,1]
	v_pk_mul_f32 v[6:7], v[0:1], v[36:37]
	v_pk_fma_f32 v[6:7], v[2:3], v[38:39], v[6:7]
	v_add_f32_e32 v198, v6, v7
	ds_read2st64_b32 v[18:19], v90 offset0:113 offset1:119
	s_cmp_lt_u32 s28, 15
	s_cbranch_scc0 .Lls0_skip1
	global_load_dwordx4 v[112:115], v174, s[12:13] nt
	global_load_dwordx2 v[152:153], v175, s[14:15] nt
	global_load_dwordx2 v[154:155], v175, s[16:17] nt
	global_load_dwordx2 v[156:157], v175, s[18:19] nt
	global_load_dwordx4 v[116:119], v180, s[20:21]
	global_load_dword v171, v181, s[20:21]
	v_add_u32_e32 v174, s25, v174
	v_add_u32_e32 v175, s26, v175
	v_add_u32_e32 v180, s27, v180
	v_add_u32_e32 v181, s27, v181
.Lls0_back1:
	v_add_f32_dpp v183, v183, v183 row_ror:8 row_mask:0xf bank_mask:0x3 bound_ctrl:1
	v_add_f32_dpp v183, v191, v191 row_ror:8 row_mask:0xf bank_mask:0xc bound_ctrl:1
	s_waitcnt lgkmcnt(6)
	v_pk_mul_f32 v[4:5], v[0:1], v[48:49] neg_lo:[0,1] neg_hi:[0,1]
	ds_read_b128 v[92:95], v88 offset:29696
	v_pk_fma_f32 v[4:5], v[2:3], v[50:51], v[4:5] neg_lo:[0,1,0] neg_hi:[0,1,0]
	ds_read_b128 v[84:87], v88 offset:29440
	v_pk_mul_f32 v[8:9], v[44:45], v[16:17] op_sel:[0,1] op_sel_hi:[1,1]
	v_add_f32_e32 v4, v4, v5
	ds_read_b128 v[80:83], v88 offset:29184
	v_pk_mul_f32 v[10:11], v[46:47], v[16:17] op_sel:[0,1] op_sel_hi:[1,1]
	v_add_f32_dpp v4, v4, v4 quad_perm:[1,0,3,2] row_mask:0xf bank_mask:0xf bound_ctrl:1
	ds_read_b128 v[96:99], v88 offset:29952
	v_pk_fma_f32 v[8:9], v[0:1], v[40:41], v[8:9]
	v_add_f32_dpp v4, v4, v4 quad_perm:[2,3,0,1] row_mask:0xf bank_mask:0xf bound_ctrl:1
	v_pk_fma_f32 v[10:11], v[2:3], v[42:43], v[10:11]
	v_add_f32_dpp v184, v184, v184 row_ror:8 row_mask:0xf bank_mask:0x3 bound_ctrl:1
	v_add_f32_dpp v4, v4, v4 row_ror:4 row_mask:0xf bank_mask:0xf bound_ctrl:1
	ds_read_b128 v[100:103], v88 offset:30208
	v_add_f32_dpp v184, v192, v192 row_ror:8 row_mask:0xf bank_mask:0xc bound_ctrl:1
	v_add_f32_dpp v4, v4, v4 row_ror:8 row_mask:0xf bank_mask:0xf bound_ctrl:1
	v_pk_fma_f32 v[0:1], v[4:5], v[52:53], v[8:9] op_sel_hi:[0,1,1]
	v_pk_fma_f32 v[2:3], v[4:5], v[54:55], v[10:11] op_sel_hi:[0,1,1]
	v_pk_mul_f32 v[6:7], v[0:1], v[56:57]
	v_pk_fma_f32 v[6:7], v[2:3], v[58:59], v[6:7]
	v_add_f32_e32 v199, v6, v7
	v_add_f32_dpp v185, v185, v185 row_ror:8 row_mask:0xf bank_mask:0x3 bound_ctrl:1
	v_add_f32_dpp v185, v193, v193 row_ror:8 row_mask:0xf bank_mask:0xc bound_ctrl:1
	s_waitcnt lgkmcnt(5)
	v_pk_mul_f32 v[4:5], v[0:1], v[68:69] neg_lo:[0,1] neg_hi:[0,1]
	ds_read_b128 v[28:31], v88 offset:31232
	v_pk_fma_f32 v[4:5], v[2:3], v[70:71], v[4:5] neg_lo:[0,1,0] neg_hi:[0,1,0]
	ds_read_b128 v[24:27], v88 offset:30976
	v_pk_mul_f32 v[8:9], v[64:65], v[18:19] op_sel_hi:[1,0]
	v_add_f32_e32 v4, v4, v5
	ds_read_b128 v[20:23], v88 offset:30720
	v_pk_mul_f32 v[10:11], v[66:67], v[18:19] op_sel_hi:[1,0]
	v_add_f32_dpp v4, v4, v4 quad_perm:[1,0,3,2] row_mask:0xf bank_mask:0xf bound_ctrl:1
	ds_read_b128 v[32:35], v88 offset:31488
	v_pk_fma_f32 v[8:9], v[0:1], v[60:61], v[8:9]
	v_add_f32_dpp v4, v4, v4 quad_perm:[2,3,0,1] row_mask:0xf bank_mask:0xf bound_ctrl:1
	v_pk_fma_f32 v[10:11], v[2:3], v[62:63], v[10:11]
	v_add_f32_dpp v186, v186, v186 row_ror:8 row_mask:0xf bank_mask:0x3 bound_ctrl:1
	v_add_f32_dpp v4, v4, v4 row_ror:4 row_mask:0xf bank_mask:0xf bound_ctrl:1
	ds_read_b128 v[36:39], v88 offset:31744
	v_add_f32_dpp v186, v194, v194 row_ror:8 row_mask:0xf bank_mask:0xc bound_ctrl:1
	v_add_f32_dpp v4, v4, v4 row_ror:8 row_mask:0xf bank_mask:0xf bound_ctrl:1
	v_pk_fma_f32 v[0:1], v[4:5], v[72:73], v[8:9] op_sel_hi:[0,1,1]
	v_pk_fma_f32 v[2:3], v[4:5], v[74:75], v[10:11] op_sel_hi:[0,1,1]
	v_pk_mul_f32 v[6:7], v[0:1], v[76:77]
	v_pk_fma_f32 v[6:7], v[2:3], v[78:79], v[6:7]
	v_add_f32_e32 v200, v6, v7
	ds_read2st64_b32 v[16:17], v90 offset0:125 offset1:131
	v_add_f32_dpp v187, v187, v187 row_ror:8 row_mask:0xf bank_mask:0x3 bound_ctrl:1
	v_add_f32_dpp v187, v195, v195 row_ror:8 row_mask:0xf bank_mask:0xc bound_ctrl:1
	s_waitcnt lgkmcnt(6)
	v_pk_mul_f32 v[4:5], v[0:1], v[92:93] neg_lo:[0,1] neg_hi:[0,1]
	ds_read_b128 v[48:51], v88 offset:32768
	v_pk_fma_f32 v[4:5], v[2:3], v[94:95], v[4:5] neg_lo:[0,1,0] neg_hi:[0,1,0]
	ds_read_b128 v[44:47], v88 offset:32512
	v_pk_mul_f32 v[8:9], v[84:85], v[18:19] op_sel:[0,1] op_sel_hi:[1,1]
	v_add_f32_e32 v4, v4, v5
	ds_read_b128 v[40:43], v88 offset:32256
	v_pk_mul_f32 v[10:11], v[86:87], v[18:19] op_sel:[0,1] op_sel_hi:[1,1]
	v_add_f32_dpp v4, v4, v4 quad_perm:[1,0,3,2] row_mask:0xf bank_mask:0xf bound_ctrl:1
	ds_read_b128 v[52:55], v88 offset:33024
	v_pk_fma_f32 v[8:9], v[0:1], v[80:81], v[8:9]
	v_add_f32_dpp v4, v4, v4 quad_perm:[2,3,0,1] row_mask:0xf bank_mask:0xf bound_ctrl:1
	v_pk_fma_f32 v[10:11], v[2:3], v[82:83], v[10:11]
	v_add_f32_dpp v188, v188, v188 row_ror:8 row_mask:0xf bank_mask:0x3 bound_ctrl:1
	v_add_f32_dpp v4, v4, v4 row_ror:4 row_mask:0xf bank_mask:0xf bound_ctrl:1
	ds_read_b128 v[56:59], v88 offset:33280
	v_add_f32_dpp v188, v196, v196 row_ror:8 row_mask:0xf bank_mask:0xc bound_ctrl:1
	v_add_f32_dpp v4, v4, v4 row_ror:8 row_mask:0xf bank_mask:0xf bound_ctrl:1
	v_pk_fma_f32 v[0:1], v[4:5], v[96:97], v[8:9] op_sel_hi:[0,1,1]
	v_pk_fma_f32 v[2:3], v[4:5], v[98:99], v[10:11] op_sel_hi:[0,1,1]
	v_pk_mul_f32 v[6:7], v[0:1], v[100:101]
	v_pk_fma_f32 v[6:7], v[2:3], v[102:103], v[6:7]
	v_add_f32_e32 v201, v6, v7
	v_add_f32_dpp v189, v189, v189 row_ror:8 row_mask:0xf bank_mask:0x3 bound_ctrl:1
	v_add_f32_dpp v189, v197, v197 row_ror:8 row_mask:0xf bank_mask:0xc bound_ctrl:1
	s_waitcnt lgkmcnt(5)
	v_pk_mul_f32 v[4:5], v[0:1], v[28:29] neg_lo:[0,1] neg_hi:[0,1]
	ds_read_b128 v[68:71], v88 offset:34304
	v_pk_fma_f32 v[4:5], v[2:3], v[30:31], v[4:5] neg_lo:[0,1,0] neg_hi:[0,1,0]
	ds_read_b128 v[64:67], v88 offset:34048
	v_pk_mul_f32 v[8:9], v[24:25], v[16:17] op_sel_hi:[1,0]
	v_add_f32_e32 v4, v4, v5
	ds_read_b128 v[60:63], v88 offset:33792
	v_pk_mul_f32 v[10:11], v[26:27], v[16:17] op_sel_hi:[1,0]
	v_add_f32_dpp v4, v4, v4 quad_perm:[1,0,3,2] row_mask:0xf bank_mask:0xf bound_ctrl:1
	ds_read_b128 v[72:75], v88 offset:34560
	v_pk_fma_f32 v[8:9], v[0:1], v[20:21], v[8:9]
	v_add_f32_dpp v4, v4, v4 quad_perm:[2,3,0,1] row_mask:0xf bank_mask:0xf bound_ctrl:1
	v_pk_fma_f32 v[10:11], v[2:3], v[22:23], v[10:11]
	v_add_f32_dpp v182, v182, v182 row_shl:4 row_mask:0xf bank_mask:0x5 bound_ctrl:1
	v_add_f32_dpp v4, v4, v4 row_ror:4 row_mask:0xf bank_mask:0xf bound_ctrl:1
	ds_read_b128 v[76:79], v88 offset:34816
	v_add_f32_dpp v182, v186, v186 row_shr:4 row_mask:0xf bank_mask:0xa bound_ctrl:1
	v_add_f32_dpp v4, v4, v4 row_ror:8 row_mask:0xf bank_mask:0xf bound_ctrl:1
	v_pk_fma_f32 v[0:1], v[4:5], v[32:33], v[8:9] op_sel_hi:[0,1,1]
	v_pk_fma_f32 v[2:3], v[4:5], v[34:35], v[10:11] op_sel_hi:[0,1,1]
	v_pk_mul_f32 v[6:7], v[0:1], v[36:37]
	v_pk_fma_f32 v[6:7], v[2:3], v[38:39], v[6:7]
	v_add_f32_e32 v202, v6, v7
	ds_read2st64_b32 v[18:19], v90 offset0:137 offset1:143
	v_add_f32_dpp v183, v183, v183 row_shl:4 row_mask:0xf bank_mask:0x5 bound_ctrl:1
	v_add_f32_dpp v183, v187, v187 row_shr:4 row_mask:0xf bank_mask:0xa bound_ctrl:1
	s_waitcnt vmcnt(18)
	ds_write_b128 v91, v[120:123] offset:0
	s_waitcnt lgkmcnt(7)
	v_pk_mul_f32 v[4:5], v[0:1], v[48:49] neg_lo:[0,1] neg_hi:[0,1]
	ds_read_b128 v[92:95], v88 offset:35840
	v_pk_fma_f32 v[4:5], v[2:3], v[50:51], v[4:5] neg_lo:[0,1,0] neg_hi:[0,1,0]
	ds_read_b128 v[84:87], v88 offset:35584
	v_pk_mul_f32 v[8:9], v[44:45], v[16:17] op_sel:[0,1] op_sel_hi:[1,1]
	v_add_f32_e32 v4, v4, v5
	ds_read_b128 v[80:83], v88 offset:35328
	v_pk_mul_f32 v[10:11], v[46:47], v[16:17] op_sel:[0,1] op_sel_hi:[1,1]
	v_add_f32_dpp v4, v4, v4 quad_perm:[1,0,3,2] row_mask:0xf bank_mask:0xf bound_ctrl:1
	ds_read_b128 v[96:99], v88 offset:36096
	v_pk_fma_f32 v[8:9], v[0:1], v[40:41], v[8:9]
	v_add_f32_dpp v4, v4, v4 quad_perm:[2,3,0,1] row_mask:0xf bank_mask:0xf bound_ctrl:1
	v_pk_fma_f32 v[10:11], v[2:3], v[42:43], v[10:11]
	v_add_f32_dpp v184, v184, v184 row_shl:4 row_mask:0xf bank_mask:0x5 bound_ctrl:1
	v_add_f32_dpp v4, v4, v4 row_ror:4 row_mask:0xf bank_mask:0xf bound_ctrl:1
	ds_read_b128 v[100:103], v88 offset:36352
	v_add_f32_dpp v184, v188, v188 row_shr:4 row_mask:0xf bank_mask:0xa bound_ctrl:1
	v_add_f32_dpp v4, v4, v4 row_ror:8 row_mask:0xf bank_mask:0xf bound_ctrl:1
	v_pk_fma_f32 v[0:1], v[4:5], v[52:53], v[8:9] op_sel_hi:[0,1,1]
	v_pk_fma_f32 v[2:3], v[4:5], v[54:55], v[10:11] op_sel_hi:[0,1,1]
	v_pk_mul_f32 v[6:7], v[0:1], v[56:57]
	v_pk_fma_f32 v[6:7], v[2:3], v[58:59], v[6:7]
	v_add_f32_e32 v203, v6, v7
	v_add_f32_dpp v185, v185, v185 row_shl:4 row_mask:0xf bank_mask:0x5 bound_ctrl:1
	v_add_f32_dpp v185, v189, v189 row_shr:4 row_mask:0xf bank_mask:0xa bound_ctrl:1
	ds_write_b128 v91, v[124:127] offset:1024
	ds_write_b32 v91, v172 offset:1280
	s_waitcnt lgkmcnt(8)
	v_pk_mul_f32 v[4:5], v[0:1], v[68:69] neg_lo:[0,1] neg_hi:[0,1]
	ds_read_b128 v[28:31], v88 offset:37376
	v_pk_fma_f32 v[4:5], v[2:3], v[70:71], v[4:5] neg_lo:[0,1,0] neg_hi:[0,1,0]
	ds_read_b128 v[24:27], v88 offset:37120
	v_pk_mul_f32 v[8:9], v[64:65], v[18:19] op_sel_hi:[1,0]
	v_add_f32_e32 v4, v4, v5
	ds_read_b128 v[20:23], v88 offset:36864
	v_pk_mul_f32 v[10:11], v[66:67], v[18:19] op_sel_hi:[1,0]
	v_add_f32_dpp v4, v4, v4 quad_perm:[1,0,3,2] row_mask:0xf bank_mask:0xf bound_ctrl:1
	ds_read_b128 v[32:35], v88 offset:37632
	v_pk_fma_f32 v[8:9], v[0:1], v[60:61], v[8:9]
	v_add_f32_dpp v4, v4, v4 quad_perm:[2,3,0,1] row_mask:0xf bank_mask:0xf bound_ctrl:1
	v_pk_fma_f32 v[10:11], v[2:3], v[62:63], v[10:11]
	v_add_f32_dpp v182, v182, v182 quad_perm:[1,0,3,2] row_mask:0xf bank_mask:0xf bound_ctrl:1
	v_add_f32_dpp v4, v4, v4 row_ror:4 row_mask:0xf bank_mask:0xf bound_ctrl:1
	ds_read_b128 v[36:39], v88 offset:37888
	v_add_f32_dpp v183, v183, v183 quad_perm:[1,0,3,2] row_mask:0xf bank_mask:0xf bound_ctrl:1
	v_add_f32_dpp v4, v4, v4 row_ror:8 row_mask:0xf bank_mask:0xf bound_ctrl:1
	v_pk_fma_f32 v[0:1], v[4:5], v[72:73], v[8:9] op_sel_hi:[0,1,1]
	v_pk_fma_f32 v[2:3], v[4:5], v[74:75], v[10:11] op_sel_hi:[0,1,1]
	v_pk_mul_f32 v[6:7], v[0:1], v[76:77]
	v_pk_fma_f32 v[6:7], v[2:3], v[78:79], v[6:7]
	v_add_f32_e32 v204, v6, v7
	ds_read2st64_b32 v[16:17], v90 offset0:149 offset1:155
	v_cndmask_b32_e64 v182, v182, v183, s[30:31]
	v_lshlrev_b32_e32 v176, 16, v158
	v_and_b32_e32 v177, 0xffff0000, v158
	s_waitcnt lgkmcnt(8)
	v_pk_mul_f32 v[4:5], v[0:1], v[92:93] neg_lo:[0,1] neg_hi:[0,1]
	ds_read_b128 v[48:51], v88 offset:38912
	v_pk_fma_f32 v[4:5], v[2:3], v[94:95], v[4:5] neg_lo:[0,1,0] neg_hi:[0,1,0]
	ds_read_b128 v[44:47], v88 offset:38656
	v_pk_mul_f32 v[8:9], v[84:85], v[18:19] op_sel:[0,1] op_sel_hi:[1,1]
	v_add_f32_e32 v4, v4, v5
	ds_read_b128 v[40:43], v88 offset:38400
	v_pk_mul_f32 v[10:11], v[86:87], v[18:19] op_sel:[0,1] op_sel_hi:[1,1]
	v_add_f32_dpp v4, v4, v4 quad_perm:[1,0,3,2] row_mask:0xf bank_mask:0xf bound_ctrl:1
	ds_read_b128 v[52:55], v88 offset:39168
	v_pk_fma_f32 v[8:9], v[0:1], v[80:81], v[8:9]
	v_add_f32_dpp v4, v4, v4 quad_perm:[2,3,0,1] row_mask:0xf bank_mask:0xf bound_ctrl:1
	v_pk_fma_f32 v[10:11], v[2:3], v[82:83], v[10:11]
	v_add_f32_dpp v184, v184, v184 quad_perm:[1,0,3,2] row_mask:0xf bank_mask:0xf bound_ctrl:1
	v_add_f32_dpp v4, v4, v4 row_ror:4 row_mask:0xf bank_mask:0xf bound_ctrl:1
	ds_read_b128 v[56:59], v88 offset:39424
	v_add_f32_dpp v185, v185, v185 quad_perm:[1,0,3,2] row_mask:0xf bank_mask:0xf bound_ctrl:1
	v_add_f32_dpp v4, v4, v4 row_ror:8 row_mask:0xf bank_mask:0xf bound_ctrl:1
	v_pk_fma_f32 v[0:1], v[4:5], v[96:97], v[8:9] op_sel_hi:[0,1,1]
	v_pk_fma_f32 v[2:3], v[4:5], v[98:99], v[10:11] op_sel_hi:[0,1,1]
	v_pk_mul_f32 v[6:7], v[0:1], v[100:101]
	v_pk_fma_f32 v[6:7], v[2:3], v[102:103], v[6:7]
	v_add_f32_e32 v205, v6, v7
	v_cndmask_b32_e64 v184, v184, v185, s[30:31]
	v_lshlrev_b32_e32 v178, 16, v159
	v_and_b32_e32 v179, 0xffff0000, v159
	s_waitcnt lgkmcnt(5)
	v_pk_mul_f32 v[4:5], v[0:1], v[28:29] neg_lo:[0,1] neg_hi:[0,1]
	ds_read_b128 v[68:71], v88 offset:40448
	v_pk_fma_f32 v[4:5], v[2:3], v[30:31], v[4:5] neg_lo:[0,1,0] neg_hi:[0,1,0]
	ds_read_b128 v[64:67], v88 offset:40192
	v_pk_mul_f32 v[8:9], v[24:25], v[16:17] op_sel_hi:[1,0]
	v_add_f32_e32 v4, v4, v5
	ds_read_b128 v[60:63], v88 offset:39936
	v_pk_mul_f32 v[10:11], v[26:27], v[16:17] op_sel_hi:[1,0]
	v_add_f32_dpp v4, v4, v4 quad_perm:[1,0,3,2] row_mask:0xf bank_mask:0xf bound_ctrl:1
	ds_read_b128 v[72:75], v88 offset:40704
	v_pk_fma_f32 v[8:9], v[0:1], v[20:21], v[8:9]
	v_add_f32_dpp v4, v4, v4 quad_perm:[2,3,0,1] row_mask:0xf bank_mask:0xf bound_ctrl:1
	v_pk_fma_f32 v[10:11], v[2:3], v[22:23], v[10:11]
	v_add_f32_dpp v182, v182, v182 quad_perm:[2,3,0,1] row_mask:0xf bank_mask:0xf bound_ctrl:1
	v_add_f32_dpp v4, v4, v4 row_ror:4 row_mask:0xf bank_mask:0xf bound_ctrl:1
	ds_read_b128 v[76:79], v88 offset:40960
	v_add_f32_dpp v184, v184, v184 quad_perm:[2,3,0,1] row_mask:0xf bank_mask:0xf bound_ctrl:1
	v_add_f32_dpp v4, v4, v4 row_ror:8 row_mask:0xf bank_mask:0xf bound_ctrl:1
	v_pk_fma_f32 v[0:1], v[4:5], v[32:33], v[8:9] op_sel_hi:[0,1,1]
	v_pk_fma_f32 v[2:3], v[4:5], v[34:35], v[10:11] op_sel_hi:[0,1,1]
	v_pk_mul_f32 v[6:7], v[0:1], v[36:37]
	v_pk_fma_f32 v[6:7], v[2:3], v[38:39], v[6:7]
	v_add_f32_e32 v206, v6, v7
	ds_read2st64_b32 v[18:19], v90 offset0:161 offset1:167
	v_cndmask_b32_e64 v214, v182, v184, s[34:35]
	v_cvt_pk_bf16_f32 v214, v214, v214
	ds_write_b128 v91, v[176:179] offset:256
	v_lshlrev_b32_e32 v176, 16, v160
	s_waitcnt lgkmcnt(7)
	v_pk_mul_f32 v[4:5], v[0:1], v[48:49] neg_lo:[0,1] neg_hi:[0,1]
	ds_read_b128 v[92:95], v88 offset:41984
	v_pk_fma_f32 v[4:5], v[2:3], v[50:51], v[4:5] neg_lo:[0,1,0] neg_hi:[0,1,0]
	ds_read_b128 v[84:87], v88 offset:41728
	v_pk_mul_f32 v[8:9], v[44:45], v[16:17] op_sel:[0,1] op_sel_hi:[1,1]
	v_add_f32_e32 v4, v4, v5
	ds_read_b128 v[80:83], v88 offset:41472
	v_pk_mul_f32 v[10:11], v[46:47], v[16:17] op_sel:[0,1] op_sel_hi:[1,1]
	v_add_f32_dpp v4, v4, v4 quad_perm:[1,0,3,2] row_mask:0xf bank_mask:0xf bound_ctrl:1
	ds_read_b128 v[96:99], v88 offset:42240
	v_pk_fma_f32 v[8:9], v[0:1], v[40:41], v[8:9]
	v_add_f32_dpp v4, v4, v4 quad_perm:[2,3,0,1] row_mask:0xf bank_mask:0xf bound_ctrl:1
	v_pk_fma_f32 v[10:11], v[2:3], v[42:43], v[10:11]
	s_nop 0
	v_add_f32_dpp v4, v4, v4 row_ror:4 row_mask:0xf bank_mask:0xf bound_ctrl:1
	ds_read_b128 v[100:103], v88 offset:42496
	s_nop 0
	v_add_f32_dpp v4, v4, v4 row_ror:8 row_mask:0xf bank_mask:0xf bound_ctrl:1
	v_pk_fma_f32 v[0:1], v[4:5], v[52:53], v[8:9] op_sel_hi:[0,1,1]
	v_pk_fma_f32 v[2:3], v[4:5], v[54:55], v[10:11] op_sel_hi:[0,1,1]
	v_pk_mul_f32 v[6:7], v[0:1], v[56:57]
	v_pk_fma_f32 v[6:7], v[2:3], v[58:59], v[6:7]
	v_add_f32_e32 v207, v6, v7
	global_store_short v145, v214, s[22:23]
	v_add_u32_e32 v145, s26, v145
	v_and_b32_e32 v177, 0xffff0000, v160
	v_lshlrev_b32_e32 v178, 16, v161
	s_waitcnt lgkmcnt(6)
	v_pk_mul_f32 v[4:5], v[0:1], v[68:69] neg_lo:[0,1] neg_hi:[0,1]
	ds_read_b128 v[28:31], v88 offset:43520
	v_pk_fma_f32 v[4:5], v[2:3], v[70:71], v[4:5] neg_lo:[0,1,0] neg_hi:[0,1,0]
	ds_read_b128 v[24:27], v88 offset:43264
	v_pk_mul_f32 v[8:9], v[64:65], v[18:19] op_sel_hi:[1,0]
	v_add_f32_e32 v4, v4, v5
	ds_read_b128 v[20:23], v88 offset:43008
	v_pk_mul_f32 v[10:11], v[66:67], v[18:19] op_sel_hi:[1,0]
	v_add_f32_dpp v4, v4, v4 quad_perm:[1,0,3,2] row_mask:0xf bank_mask:0xf bound_ctrl:1
	ds_read_b128 v[32:35], v88 offset:43776
	v_pk_fma_f32 v[8:9], v[0:1], v[60:61], v[8:9]
	v_add_f32_dpp v4, v4, v4 quad_perm:[2,3,0,1] row_mask:0xf bank_mask:0xf bound_ctrl:1
	v_pk_fma_f32 v[10:11], v[2:3], v[62:63], v[10:11]
	s_nop 0
	v_add_f32_dpp v4, v4, v4 row_ror:4 row_mask:0xf bank_mask:0xf bound_ctrl:1
	ds_read_b128 v[36:39], v88 offset:44032
	s_nop 0
	v_add_f32_dpp v4, v4, v4 row_ror:8 row_mask:0xf bank_mask:0xf bound_ctrl:1
	v_pk_fma_f32 v[0:1], v[4:5], v[72:73], v[8:9] op_sel_hi:[0,1,1]
	v_pk_fma_f32 v[2:3], v[4:5], v[74:75], v[10:11] op_sel_hi:[0,1,1]
	v_pk_mul_f32 v[6:7], v[0:1], v[76:77]
	v_pk_fma_f32 v[6:7], v[2:3], v[78:79], v[6:7]
	v_add_f32_e32 v208, v6, v7
	ds_read2st64_b32 v[16:17], v90 offset0:173 offset1:179
	v_and_b32_e32 v179, 0xffff0000, v161
	ds_write_b128 v91, v[176:179] offset:512
	s_waitcnt lgkmcnt(7)
	v_pk_mul_f32 v[4:5], v[0:1], v[92:93] neg_lo:[0,1] neg_hi:[0,1]
	ds_read_b128 v[48:51], v88 offset:45056
	v_pk_fma_f32 v[4:5], v[2:3], v[94:95], v[4:5] neg_lo:[0,1,0] neg_hi:[0,1,0]
	ds_read_b128 v[44:47], v88 offset:44800
	v_pk_mul_f32 v[8:9], v[84:85], v[18:19] op_sel:[0,1] op_sel_hi:[1,1]
	v_add_f32_e32 v4, v4, v5
	ds_read_b128 v[40:43], v88 offset:44544
	v_pk_mul_f32 v[10:11], v[86:87], v[18:19] op_sel:[0,1] op_sel_hi:[1,1]
	v_add_f32_dpp v4, v4, v4 quad_perm:[1,0,3,2] row_mask:0xf bank_mask:0xf bound_ctrl:1
	ds_read_b128 v[52:55], v88 offset:45312
	v_pk_fma_f32 v[8:9], v[0:1], v[80:81], v[8:9]
	v_add_f32_dpp v4, v4, v4 quad_perm:[2,3,0,1] row_mask:0xf bank_mask:0xf bound_ctrl:1
	v_pk_fma_f32 v[10:11], v[2:3], v[82:83], v[10:11]
	s_nop 0
	v_add_f32_dpp v4, v4, v4 row_ror:4 row_mask:0xf bank_mask:0xf bound_ctrl:1
	ds_read_b128 v[56:59], v88 offset:45568
	s_nop 0
	v_add_f32_dpp v4, v4, v4 row_ror:8 row_mask:0xf bank_mask:0xf bound_ctrl:1
	v_pk_fma_f32 v[0:1], v[4:5], v[96:97], v[8:9] op_sel_hi:[0,1,1]
	v_pk_fma_f32 v[2:3], v[4:5], v[98:99], v[10:11] op_sel_hi:[0,1,1]
	v_pk_mul_f32 v[6:7], v[0:1], v[100:101]
	v_pk_fma_f32 v[6:7], v[2:3], v[102:103], v[6:7]
	v_add_f32_e32 v209, v6, v7
	v_lshlrev_b32_e32 v176, 16, v162
	v_and_b32_e32 v177, 0xffff0000, v162
	s_waitcnt lgkmcnt(6)
	v_pk_mul_f32 v[4:5], v[0:1], v[28:29] neg_lo:[0,1] neg_hi:[0,1]
	ds_read_b128 v[68:71], v88 offset:46592
	v_pk_fma_f32 v[4:5], v[2:3], v[30:31], v[4:5] neg_lo:[0,1,0] neg_hi:[0,1,0]
	ds_read_b128 v[64:67], v88 offset:46336
	v_pk_mul_f32 v[8:9], v[24:25], v[16:17] op_sel_hi:[1,0]
	v_add_f32_e32 v4, v4, v5
	ds_read_b128 v[60:63], v88 offset:46080
	v_pk_mul_f32 v[10:11], v[26:27], v[16:17] op_sel_hi:[1,0]
	v_add_f32_dpp v4, v4, v4 quad_perm:[1,0,3,2] row_mask:0xf bank_mask:0xf bound_ctrl:1
	ds_read_b128 v[72:75], v88 offset:46848
	v_pk_fma_f32 v[8:9], v[0:1], v[20:21], v[8:9]
	v_add_f32_dpp v4, v4, v4 quad_perm:[2,3,0,1] row_mask:0xf bank_mask:0xf bound_ctrl:1
	v_pk_fma_f32 v[10:11], v[2:3], v[22:23], v[10:11]
	s_nop 0
	v_add_f32_dpp v4, v4, v4 row_ror:4 row_mask:0xf bank_mask:0xf bound_ctrl:1
	ds_read_b128 v[76:79], v88 offset:47104
	s_nop 0
	v_add_f32_dpp v4, v4, v4 row_ror:8 row_mask:0xf bank_mask:0xf bound_ctrl:1
	v_pk_fma_f32 v[0:1], v[4:5], v[32:33], v[8:9] op_sel_hi:[0,1,1]
	v_pk_fma_f32 v[2:3], v[4:5], v[34:35], v[10:11] op_sel_hi:[0,1,1]
	v_pk_mul_f32 v[6:7], v[0:1], v[36:37]
	v_pk_fma_f32 v[6:7], v[2:3], v[38:39], v[6:7]
	v_add_f32_e32 v210, v6, v7
	ds_read2st64_b32 v[18:19], v90 offset0:185 offset1:191
	v_lshlrev_b32_e32 v178, 16, v163
	v_and_b32_e32 v179, 0xffff0000, v163
	ds_write_b128 v91, v[176:179] offset:768
	s_waitcnt lgkmcnt(7)
	v_pk_mul_f32 v[4:5], v[0:1], v[48:49] neg_lo:[0,1] neg_hi:[0,1]
	ds_read_b128 v[92:95], v88 offset:48128
	v_pk_fma_f32 v[4:5], v[2:3], v[50:51], v[4:5] neg_lo:[0,1,0] neg_hi:[0,1,0]
	ds_read_b128 v[84:87], v88 offset:47872
	v_pk_mul_f32 v[8:9], v[44:45], v[16:17] op_sel:[0,1] op_sel_hi:[1,1]
	v_add_f32_e32 v4, v4, v5
	ds_read_b128 v[80:83], v88 offset:47616
	v_pk_mul_f32 v[10:11], v[46:47], v[16:17] op_sel:[0,1] op_sel_hi:[1,1]
	v_add_f32_dpp v4, v4, v4 quad_perm:[1,0,3,2] row_mask:0xf bank_mask:0xf bound_ctrl:1
	ds_read_b128 v[96:99], v88 offset:48384
	v_pk_fma_f32 v[8:9], v[0:1], v[40:41], v[8:9]
	v_add_f32_dpp v4, v4, v4 quad_perm:[2,3,0,1] row_mask:0xf bank_mask:0xf bound_ctrl:1
	v_pk_fma_f32 v[10:11], v[2:3], v[42:43], v[10:11]
	s_nop 0
	v_add_f32_dpp v4, v4, v4 row_ror:4 row_mask:0xf bank_mask:0xf bound_ctrl:1
	ds_read_b128 v[100:103], v88 offset:48640
	s_nop 0
	v_add_f32_dpp v4, v4, v4 row_ror:8 row_mask:0xf bank_mask:0xf bound_ctrl:1
	v_pk_fma_f32 v[0:1], v[4:5], v[52:53], v[8:9] op_sel_hi:[0,1,1]
	v_pk_fma_f32 v[2:3], v[4:5], v[54:55], v[10:11] op_sel_hi:[0,1,1]
	v_pk_mul_f32 v[6:7], v[0:1], v[56:57]
	v_pk_fma_f32 v[6:7], v[2:3], v[58:59], v[6:7]
	v_add_f32_e32 v211, v6, v7
	s_waitcnt lgkmcnt(0)
	s_barrier
	v_pk_mul_f32 v[4:5], v[0:1], v[68:69] neg_lo:[0,1] neg_hi:[0,1]
	ds_read_b128 v[28:31], v88 offset:512
	v_pk_fma_f32 v[4:5], v[2:3], v[70:71], v[4:5] neg_lo:[0,1,0] neg_hi:[0,1,0]
	ds_read_b128 v[24:27], v88 offset:256
	v_pk_mul_f32 v[8:9], v[64:65], v[18:19] op_sel_hi:[1,0]
	v_add_f32_e32 v4, v4, v5
	ds_read_b128 v[20:23], v88 offset:0
	v_pk_mul_f32 v[10:11], v[66:67], v[18:19] op_sel_hi:[1,0]
	v_add_f32_dpp v4, v4, v4 quad_perm:[1,0,3,2] row_mask:0xf bank_mask:0xf bound_ctrl:1
	ds_read_b128 v[32:35], v88 offset:768
	v_pk_fma_f32 v[8:9], v[0:1], v[60:61], v[8:9]
	v_add_f32_dpp v4, v4, v4 quad_perm:[2,3,0,1] row_mask:0xf bank_mask:0xf bound_ctrl:1
	v_pk_fma_f32 v[10:11], v[2:3], v[62:63], v[10:11]
	s_nop 0
	v_add_f32_dpp v4, v4, v4 row_ror:4 row_mask:0xf bank_mask:0xf bound_ctrl:1
	ds_read_b128 v[36:39], v88 offset:1024
	s_nop 0
	v_add_f32_dpp v4, v4, v4 row_ror:8 row_mask:0xf bank_mask:0xf bound_ctrl:1
	v_pk_fma_f32 v[0:1], v[4:5], v[72:73], v[8:9] op_sel_hi:[0,1,1]
	v_pk_fma_f32 v[2:3], v[4:5], v[74:75], v[10:11] op_sel_hi:[0,1,1]
	v_pk_mul_f32 v[6:7], v[0:1], v[76:77]
	v_pk_fma_f32 v[6:7], v[2:3], v[78:79], v[6:7]
	v_add_f32_e32 v212, v6, v7
	ds_read2st64_b32 v[16:17], v90 offset0:5 offset1:11
	s_waitcnt lgkmcnt(6)
	v_pk_mul_f32 v[4:5], v[0:1], v[92:93] neg_lo:[0,1] neg_hi:[0,1]
	ds_read_b128 v[48:51], v88 offset:2048
	v_pk_fma_f32 v[4:5], v[2:3], v[94:95], v[4:5] neg_lo:[0,1,0] neg_hi:[0,1,0]
	ds_read_b128 v[44:47], v88 offset:1792
	v_pk_mul_f32 v[8:9], v[84:85], v[18:19] op_sel:[0,1] op_sel_hi:[1,1]
	v_add_f32_e32 v4, v4, v5
	ds_read_b128 v[40:43], v88 offset:1536
	v_pk_mul_f32 v[10:11], v[86:87], v[18:19] op_sel:[0,1] op_sel_hi:[1,1]
	v_add_f32_dpp v4, v4, v4 quad_perm:[1,0,3,2] row_mask:0xf bank_mask:0xf bound_ctrl:1
	ds_read_b128 v[52:55], v88 offset:2304
	v_pk_fma_f32 v[8:9], v[0:1], v[80:81], v[8:9]
	v_add_f32_dpp v4, v4, v4 quad_perm:[2,3,0,1] row_mask:0xf bank_mask:0xf bound_ctrl:1
	v_pk_fma_f32 v[10:11], v[2:3], v[82:83], v[10:11]
	s_nop 0
	v_add_f32_dpp v4, v4, v4 row_ror:4 row_mask:0xf bank_mask:0xf bound_ctrl:1
	ds_read_b128 v[56:59], v88 offset:2560
	s_nop 0
	v_add_f32_dpp v4, v4, v4 row_ror:8 row_mask:0xf bank_mask:0xf bound_ctrl:1
	v_pk_fma_f32 v[0:1], v[4:5], v[96:97], v[8:9] op_sel_hi:[0,1,1]
	v_pk_fma_f32 v[2:3], v[4:5], v[98:99], v[10:11] op_sel_hi:[0,1,1]
	v_pk_mul_f32 v[6:7], v[0:1], v[100:101]
	v_pk_fma_f32 v[6:7], v[2:3], v[102:103], v[6:7]
	v_add_f32_e32 v213, v6, v7
	s_waitcnt lgkmcnt(5)
	v_pk_mul_f32 v[4:5], v[0:1], v[28:29] neg_lo:[0,1] neg_hi:[0,1]
	ds_read_b128 v[68:71], v88 offset:3584
	v_pk_fma_f32 v[4:5], v[2:3], v[30:31], v[4:5] neg_lo:[0,1,0] neg_hi:[0,1,0]
	ds_read_b128 v[64:67], v88 offset:3328
	v_pk_mul_f32 v[8:9], v[24:25], v[16:17] op_sel_hi:[1,0]
	v_add_f32_e32 v4, v4, v5
	ds_read_b128 v[60:63], v88 offset:3072
	v_pk_mul_f32 v[10:11], v[26:27], v[16:17] op_sel_hi:[1,0]
	v_add_f32_dpp v4, v4, v4 quad_perm:[1,0,3,2] row_mask:0xf bank_mask:0xf bound_ctrl:1
	ds_read_b128 v[72:75], v88 offset:3840
	v_pk_fma_f32 v[8:9], v[0:1], v[20:21], v[8:9]
	v_add_f32_dpp v4, v4, v4 quad_perm:[2,3,0,1] row_mask:0xf bank_mask:0xf bound_ctrl:1
	v_pk_fma_f32 v[10:11], v[2:3], v[22:23], v[10:11]
	v_add_f32_dpp v198, v198, v198 row_ror:8 row_mask:0xf bank_mask:0x3 bound_ctrl:1
	v_add_f32_dpp v4, v4, v4 row_ror:4 row_mask:0xf bank_mask:0xf bound_ctrl:1
	ds_read_b128 v[76:79], v88 offset:4096
	v_add_f32_dpp v198, v206, v206 row_ror:8 row_mask:0xf bank_mask:0xc bound_ctrl:1
	v_add_f32_dpp v4, v4, v4 row_ror:8 row_mask:0xf bank_mask:0xf bound_ctrl:1
	v_pk_fma_f32 v[0:1], v[4:5], v[32:33], v[8:9] op_sel_hi:[0,1,1]
	v_pk_fma_f32 v[2:3], v[4:5], v[34:35], v[10:11] op_sel_hi:[0,1,1]
	v_pk_mul_f32 v[6:7], v[0:1], v[36:37]
	v_pk_fma_f32 v[6:7], v[2:3], v[38:39], v[6:7]
	v_add_f32_e32 v182, v6, v7
	ds_read2st64_b32 v[18:19], v90 offset0:17 offset1:23
	s_cmp_lt_u32 s28, 15
	s_cbranch_scc0 .Lls0_skip2
	global_load_dwordx4 v[120:123], v174, s[12:13] nt
	global_load_dwordx2 v[158:159], v175, s[14:15] nt
	global_load_dwordx2 v[160:161], v175, s[16:17] nt
	global_load_dwordx2 v[162:163], v175, s[18:19] nt
	global_load_dwordx4 v[124:127], v180, s[20:21]
	global_load_dword v172, v181, s[20:21]
	v_add_u32_e32 v174, s25, v174
	v_add_u32_e32 v175, s26, v175
	v_add_u32_e32 v180, s27, v180
	v_add_u32_e32 v181, s27, v181
.Lls0_back2:
	v_add_f32_dpp v199, v199, v199 row_ror:8 row_mask:0xf bank_mask:0x3 bound_ctrl:1
	v_add_f32_dpp v199, v207, v207 row_ror:8 row_mask:0xf bank_mask:0xc bound_ctrl:1
	s_waitcnt lgkmcnt(6)
	v_pk_mul_f32 v[4:5], v[0:1], v[48:49] neg_lo:[0,1] neg_hi:[0,1]
	ds_read_b128 v[92:95], v88 offset:5120
	v_pk_fma_f32 v[4:5], v[2:3], v[50:51], v[4:5] neg_lo:[0,1,0] neg_hi:[0,1,0]
	ds_read_b128 v[84:87], v88 offset:4864
	v_pk_mul_f32 v[8:9], v[44:45], v[16:17] op_sel:[0,1] op_sel_hi:[1,1]
	v_add_f32_e32 v4, v4, v5
	ds_read_b128 v[80:83], v88 offset:4608
	v_pk_mul_f32 v[10:11], v[46:47], v[16:17] op_sel:[0,1] op_sel_hi:[1,1]
	v_add_f32_dpp v4, v4, v4 quad_perm:[1,0,3,2] row_mask:0xf bank_mask:0xf bound_ctrl:1
	ds_read_b128 v[96:99], v88 offset:5376
	v_pk_fma_f32 v[8:9], v[0:1], v[40:41], v[8:9]
	v_add_f32_dpp v4, v4, v4 quad_perm:[2,3,0,1] row_mask:0xf bank_mask:0xf bound_ctrl:1
	v_pk_fma_f32 v[10:11], v[2:3], v[42:43], v[10:11]
	v_add_f32_dpp v200, v200, v200 row_ror:8 row_mask:0xf bank_mask:0x3 bound_ctrl:1
	v_add_f32_dpp v4, v4, v4 row_ror:4 row_mask:0xf bank_mask:0xf bound_ctrl:1
	ds_read_b128 v[100:103], v88 offset:5632
	v_add_f32_dpp v200, v208, v208 row_ror:8 row_mask:0xf bank_mask:0xc bound_ctrl:1
	v_add_f32_dpp v4, v4, v4 row_ror:8 row_mask:0xf bank_mask:0xf bound_ctrl:1
	v_pk_fma_f32 v[0:1], v[4:5], v[52:53], v[8:9] op_sel_hi:[0,1,1]
	v_pk_fma_f32 v[2:3], v[4:5], v[54:55], v[10:11] op_sel_hi:[0,1,1]
	v_pk_mul_f32 v[6:7], v[0:1], v[56:57]
	v_pk_fma_f32 v[6:7], v[2:3], v[58:59], v[6:7]
	v_add_f32_e32 v183, v6, v7
	v_add_f32_dpp v201, v201, v201 row_ror:8 row_mask:0xf bank_mask:0x3 bound_ctrl:1
	v_add_f32_dpp v201, v209, v209 row_ror:8 row_mask:0xf bank_mask:0xc bound_ctrl:1
	s_waitcnt lgkmcnt(5)
	v_pk_mul_f32 v[4:5], v[0:1], v[68:69] neg_lo:[0,1] neg_hi:[0,1]
	ds_read_b128 v[28:31], v88 offset:6656
	v_pk_fma_f32 v[4:5], v[2:3], v[70:71], v[4:5] neg_lo:[0,1,0] neg_hi:[0,1,0]
	ds_read_b128 v[24:27], v88 offset:6400
	v_pk_mul_f32 v[8:9], v[64:65], v[18:19] op_sel_hi:[1,0]
	v_add_f32_e32 v4, v4, v5
	ds_read_b128 v[20:23], v88 offset:6144
	v_pk_mul_f32 v[10:11], v[66:67], v[18:19] op_sel_hi:[1,0]
	v_add_f32_dpp v4, v4, v4 quad_perm:[1,0,3,2] row_mask:0xf bank_mask:0xf bound_ctrl:1
	ds_read_b128 v[32:35], v88 offset:6912
	v_pk_fma_f32 v[8:9], v[0:1], v[60:61], v[8:9]
	v_add_f32_dpp v4, v4, v4 quad_perm:[2,3,0,1] row_mask:0xf bank_mask:0xf bound_ctrl:1
	v_pk_fma_f32 v[10:11], v[2:3], v[62:63], v[10:11]
	v_add_f32_dpp v202, v202, v202 row_ror:8 row_mask:0xf bank_mask:0x3 bound_ctrl:1
	v_add_f32_dpp v4, v4, v4 row_ror:4 row_mask:0xf bank_mask:0xf bound_ctrl:1
	ds_read_b128 v[36:39], v88 offset:7168
	v_add_f32_dpp v202, v210, v210 row_ror:8 row_mask:0xf bank_mask:0xc bound_ctrl:1
	v_add_f32_dpp v4, v4, v4 row_ror:8 row_mask:0xf bank_mask:0xf bound_ctrl:1
	v_pk_fma_f32 v[0:1], v[4:5], v[72:73], v[8:9] op_sel_hi:[0,1,1]
	v_pk_fma_f32 v[2:3], v[4:5], v[74:75], v[10:11] op_sel_hi:[0,1,1]
	v_pk_mul_f32 v[6:7], v[0:1], v[76:77]
	v_pk_fma_f32 v[6:7], v[2:3], v[78:79], v[6:7]
	v_add_f32_e32 v184, v6, v7
	ds_read2st64_b32 v[16:17], v90 offset0:29 offset1:35
	v_add_f32_dpp v203, v203, v203 row_ror:8 row_mask:0xf bank_mask:0x3 bound_ctrl:1
	v_add_f32_dpp v203, v211, v211 row_ror:8 row_mask:0xf bank_mask:0xc bound_ctrl:1
	s_waitcnt lgkmcnt(6)
	v_pk_mul_f32 v[4:5], v[0:1], v[92:93] neg_lo:[0,1] neg_hi:[0,1]
	ds_read_b128 v[48:51], v88 offset:8192
	v_pk_fma_f32 v[4:5], v[2:3], v[94:95], v[4:5] neg_lo:[0,1,0] neg_hi:[0,1,0]
	ds_read_b128 v[44:47], v88 offset:7936
	v_pk_mul_f32 v[8:9], v[84:85], v[18:19] op_sel:[0,1] op_sel_hi:[1,1]
	v_add_f32_e32 v4, v4, v5
	ds_read_b128 v[40:43], v88 offset:7680
	v_pk_mul_f32 v[10:11], v[86:87], v[18:19] op_sel:[0,1] op_sel_hi:[1,1]
	v_add_f32_dpp v4, v4, v4 quad_perm:[1,0,3,2] row_mask:0xf bank_mask:0xf bound_ctrl:1
	ds_read_b128 v[52:55], v88 offset:8448
	v_pk_fma_f32 v[8:9], v[0:1], v[80:81], v[8:9]
	v_add_f32_dpp v4, v4, v4 quad_perm:[2,3,0,1] row_mask:0xf bank_mask:0xf bound_ctrl:1
	v_pk_fma_f32 v[10:11], v[2:3], v[82:83], v[10:11]
	v_add_f32_dpp v204, v204, v204 row_ror:8 row_mask:0xf bank_mask:0x3 bound_ctrl:1
	v_add_f32_dpp v4, v4, v4 row_ror:4 row_mask:0xf bank_mask:0xf bound_ctrl:1
	ds_read_b128 v[56:59], v88 offset:8704
	v_add_f32_dpp v204, v212, v212 row_ror:8 row_mask:0xf bank_mask:0xc bound_ctrl:1
	v_add_f32_dpp v4, v4, v4 row_ror:8 row_mask:0xf bank_mask:0xf bound_ctrl:1
	v_pk_fma_f32 v[0:1], v[4:5], v[96:97], v[8:9] op_sel_hi:[0,1,1]
	v_pk_fma_f32 v[2:3], v[4:5], v[98:99], v[10:11] op_sel_hi:[0,1,1]
	v_pk_mul_f32 v[6:7], v[0:1], v[100:101]
	v_pk_fma_f32 v[6:7], v[2:3], v[102:103], v[6:7]
	v_add_f32_e32 v185, v6, v7
	v_add_f32_dpp v205, v205, v205 row_ror:8 row_mask:0xf bank_mask:0x3 bound_ctrl:1
	v_add_f32_dpp v205, v213, v213 row_ror:8 row_mask:0xf bank_mask:0xc bound_ctrl:1
	s_waitcnt lgkmcnt(5)
	v_pk_mul_f32 v[4:5], v[0:1], v[28:29] neg_lo:[0,1] neg_hi:[0,1]
	ds_read_b128 v[68:71], v88 offset:9728
	v_pk_fma_f32 v[4:5], v[2:3], v[30:31], v[4:5] neg_lo:[0,1,0] neg_hi:[0,1,0]
	ds_read_b128 v[64:67], v88 offset:9472
	v_pk_mul_f32 v[8:9], v[24:25], v[16:17] op_sel_hi:[1,0]
	v_add_f32_e32 v4, v4, v5
	ds_read_b128 v[60:63], v88 offset:9216
	v_pk_mul_f32 v[10:11], v[26:27], v[16:17] op_sel_hi:[1,0]
	v_add_f32_dpp v4, v4, v4 quad_perm:[1,0,3,2] row_mask:0xf bank_mask:0xf bound_ctrl:1
	ds_read_b128 v[72:75], v88 offset:9984
	v_pk_fma_f32 v[8:9], v[0:1], v[20:21], v[8:9]
	v_add_f32_dpp v4, v4, v4 quad_perm:[2,3,0,1] row_mask:0xf bank_mask:0xf bound_ctrl:1
	v_pk_fma_f32 v[10:11], v[2:3], v[22:23], v[10:11]
	v_add_f32_dpp v198, v198, v198 row_shl:4 row_mask:0xf bank_mask:0x5 bound_ctrl:1
	v_add_f32_dpp v4, v4, v4 row_ror:4 row_mask:0xf bank_mask:0xf bound_ctrl:1
	ds_read_b128 v[76:79], v88 offset:10240
	v_add_f32_dpp v198, v202, v202 row_shr:4 row_mask:0xf bank_mask:0xa bound_ctrl:1
	v_add_f32_dpp v4, v4, v4 row_ror:8 row_mask:0xf bank_mask:0xf bound_ctrl:1
	v_pk_fma_f32 v[0:1], v[4:5], v[32:33], v[8:9] op_sel_hi:[0,1,1]
	v_pk_fma_f32 v[2:3], v[4:5], v[34:35], v[10:11] op_sel_hi:[0,1,1]
	v_pk_mul_f32 v[6:7], v[0:1], v[36:37]
	v_pk_fma_f32 v[6:7], v[2:3], v[38:39], v[6:7]
	v_add_f32_e32 v186, v6, v7
	ds_read2st64_b32 v[18:19], v90 offset0:41 offset1:47
	v_add_f32_dpp v199, v199, v199 row_shl:4 row_mask:0xf bank_mask:0x5 bound_ctrl:1
	v_add_f32_dpp v199, v203, v203 row_shr:4 row_mask:0xf bank_mask:0xa bound_ctrl:1
	s_waitcnt vmcnt(19)
	ds_write_b128 v91, v[128:131] offset:24576
	s_waitcnt lgkmcnt(7)
	v_pk_mul_f32 v[4:5], v[0:1], v[48:49] neg_lo:[0,1] neg_hi:[0,1]
	ds_read_b128 v[92:95], v88 offset:11264
	v_pk_fma_f32 v[4:5], v[2:3], v[50:51], v[4:5] neg_lo:[0,1,0] neg_hi:[0,1,0]
	ds_read_b128 v[84:87], v88 offset:11008
	v_pk_mul_f32 v[8:9], v[44:45], v[16:17] op_sel:[0,1] op_sel_hi:[1,1]
	v_add_f32_e32 v4, v4, v5
	ds_read_b128 v[80:83], v88 offset:10752
	v_pk_mul_f32 v[10:11], v[46:47], v[16:17] op_sel:[0,1] op_sel_hi:[1,1]
	v_add_f32_dpp v4, v4, v4 quad_perm:[1,0,3,2] row_mask:0xf bank_mask:0xf bound_ctrl:1
	ds_read_b128 v[96:99], v88 offset:11520
	v_pk_fma_f32 v[8:9], v[0:1], v[40:41], v[8:9]
	v_add_f32_dpp v4, v4, v4 quad_perm:[2,3,0,1] row_mask:0xf bank_mask:0xf bound_ctrl:1
	v_pk_fma_f32 v[10:11], v[2:3], v[42:43], v[10:11]
	v_add_f32_dpp v200, v200, v200 row_shl:4 row_mask:0xf bank_mask:0x5 bound_ctrl:1
	v_add_f32_dpp v4, v4, v4 row_ror:4 row_mask:0xf bank_mask:0xf bound_ctrl:1
	ds_read_b128 v[100:103], v88 offset:11776
	v_add_f32_dpp v200, v204, v204 row_shr:4 row_mask:0xf bank_mask:0xa bound_ctrl:1
	v_add_f32_dpp v4, v4, v4 row_ror:8 row_mask:0xf bank_mask:0xf bound_ctrl:1
	v_pk_fma_f32 v[0:1], v[4:5], v[52:53], v[8:9] op_sel_hi:[0,1,1]
	v_pk_fma_f32 v[2:3], v[4:5], v[54:55], v[10:11] op_sel_hi:[0,1,1]
	v_pk_mul_f32 v[6:7], v[0:1], v[56:57]
	v_pk_fma_f32 v[6:7], v[2:3], v[58:59], v[6:7]
	v_add_f32_e32 v187, v6, v7
	v_add_f32_dpp v201, v201, v201 row_shl:4 row_mask:0xf bank_mask:0x5 bound_ctrl:1
	v_add_f32_dpp v201, v205, v205 row_shr:4 row_mask:0xf bank_mask:0xa bound_ctrl:1
	ds_write_b128 v91, v[132:135] offset:25600
	ds_write_b32 v91, v173 offset:25856
	s_waitcnt lgkmcnt(8)
	v_pk_mul_f32 v[4:5], v[0:1], v[68:69] neg_lo:[0,1] neg_hi:[0,1]
	ds_read_b128 v[28:31], v88 offset:12800
	v_pk_fma_f32 v[4:5], v[2:3], v[70:71], v[4:5] neg_lo:[0,1,0] neg_hi:[0,1,0]
	ds_read_b128 v[24:27], v88 offset:12544
	v_pk_mul_f32 v[8:9], v[64:65], v[18:19] op_sel_hi:[1,0]
	v_add_f32_e32 v4, v4, v5
	ds_read_b128 v[20:23], v88 offset:12288
	v_pk_mul_f32 v[10:11], v[66:67], v[18:19] op_sel_hi:[1,0]
	v_add_f32_dpp v4, v4, v4 quad_perm:[1,0,3,2] row_mask:0xf bank_mask:0xf bound_ctrl:1
	ds_read_b128 v[32:35], v88 offset:13056
	v_pk_fma_f32 v[8:9], v[0:1], v[60:61], v[8:9]
	v_add_f32_dpp v4, v4, v4 quad_perm:[2,3,0,1] row_mask:0xf bank_mask:0xf bound_ctrl:1
	v_pk_fma_f32 v[10:11], v[2:3], v[62:63], v[10:11]
	v_add_f32_dpp v198, v198, v198 quad_perm:[1,0,3,2] row_mask:0xf bank_mask:0xf bound_ctrl:1
	v_add_f32_dpp v4, v4, v4 row_ror:4 row_mask:0xf bank_mask:0xf bound_ctrl:1
	ds_read_b128 v[36:39], v88 offset:13312
	v_add_f32_dpp v199, v199, v199 quad_perm:[1,0,3,2] row_mask:0xf bank_mask:0xf bound_ctrl:1
	v_add_f32_dpp v4, v4, v4 row_ror:8 row_mask:0xf bank_mask:0xf bound_ctrl:1
	v_pk_fma_f32 v[0:1], v[4:5], v[72:73], v[8:9] op_sel_hi:[0,1,1]
	v_pk_fma_f32 v[2:3], v[4:5], v[74:75], v[10:11] op_sel_hi:[0,1,1]
	v_pk_mul_f32 v[6:7], v[0:1], v[76:77]
	v_pk_fma_f32 v[6:7], v[2:3], v[78:79], v[6:7]
	v_add_f32_e32 v188, v6, v7
	ds_read2st64_b32 v[16:17], v90 offset0:53 offset1:59
	v_cndmask_b32_e64 v198, v198, v199, s[30:31]
	v_lshlrev_b32_e32 v176, 16, v164
	v_and_b32_e32 v177, 0xffff0000, v164
	s_waitcnt lgkmcnt(8)
	v_pk_mul_f32 v[4:5], v[0:1], v[92:93] neg_lo:[0,1] neg_hi:[0,1]
	ds_read_b128 v[48:51], v88 offset:14336
	v_pk_fma_f32 v[4:5], v[2:3], v[94:95], v[4:5] neg_lo:[0,1,0] neg_hi:[0,1,0]
	ds_read_b128 v[44:47], v88 offset:14080
	v_pk_mul_f32 v[8:9], v[84:85], v[18:19] op_sel:[0,1] op_sel_hi:[1,1]
	v_add_f32_e32 v4, v4, v5
	ds_read_b128 v[40:43], v88 offset:13824
	v_pk_mul_f32 v[10:11], v[86:87], v[18:19] op_sel:[0,1] op_sel_hi:[1,1]
	v_add_f32_dpp v4, v4, v4 quad_perm:[1,0,3,2] row_mask:0xf bank_mask:0xf bound_ctrl:1
	ds_read_b128 v[52:55], v88 offset:14592
	v_pk_fma_f32 v[8:9], v[0:1], v[80:81], v[8:9]
	v_add_f32_dpp v4, v4, v4 quad_perm:[2,3,0,1] row_mask:0xf bank_mask:0xf bound_ctrl:1
	v_pk_fma_f32 v[10:11], v[2:3], v[82:83], v[10:11]
	v_add_f32_dpp v200, v200, v200 quad_perm:[1,0,3,2] row_mask:0xf bank_mask:0xf bound_ctrl:1
	v_add_f32_dpp v4, v4, v4 row_ror:4 row_mask:0xf bank_mask:0xf bound_ctrl:1
	ds_read_b128 v[56:59], v88 offset:14848
	v_add_f32_dpp v201, v201, v201 quad_perm:[1,0,3,2] row_mask:0xf bank_mask:0xf bound_ctrl:1
	v_add_f32_dpp v4, v4, v4 row_ror:8 row_mask:0xf bank_mask:0xf bound_ctrl:1
	v_pk_fma_f32 v[0:1], v[4:5], v[96:97], v[8:9] op_sel_hi:[0,1,1]
	v_pk_fma_f32 v[2:3], v[4:5], v[98:99], v[10:11] op_sel_hi:[0,1,1]
	v_pk_mul_f32 v[6:7], v[0:1], v[100:101]
	v_pk_fma_f32 v[6:7], v[2:3], v[102:103], v[6:7]
	v_add_f32_e32 v189, v6, v7
	v_cndmask_b32_e64 v200, v200, v201, s[30:31]
	v_lshlrev_b32_e32 v178, 16, v165
	v_and_b32_e32 v179, 0xffff0000, v165
	s_waitcnt lgkmcnt(5)
	v_pk_mul_f32 v[4:5], v[0:1], v[28:29] neg_lo:[0,1] neg_hi:[0,1]
	ds_read_b128 v[68:71], v88 offset:15872
	v_pk_fma_f32 v[4:5], v[2:3], v[30:31], v[4:5] neg_lo:[0,1,0] neg_hi:[0,1,0]
	ds_read_b128 v[64:67], v88 offset:15616
	v_pk_mul_f32 v[8:9], v[24:25], v[16:17] op_sel_hi:[1,0]
	v_add_f32_e32 v4, v4, v5
	ds_read_b128 v[60:63], v88 offset:15360
	v_pk_mul_f32 v[10:11], v[26:27], v[16:17] op_sel_hi:[1,0]
	v_add_f32_dpp v4, v4, v4 quad_perm:[1,0,3,2] row_mask:0xf bank_mask:0xf bound_ctrl:1
	ds_read_b128 v[72:75], v88 offset:16128
	v_pk_fma_f32 v[8:9], v[0:1], v[20:21], v[8:9]
	v_add_f32_dpp v4, v4, v4 quad_perm:[2,3,0,1] row_mask:0xf bank_mask:0xf bound_ctrl:1
	v_pk_fma_f32 v[10:11], v[2:3], v[22:23], v[10:11]
	v_add_f32_dpp v198, v198, v198 quad_perm:[2,3,0,1] row_mask:0xf bank_mask:0xf bound_ctrl:1
	v_add_f32_dpp v4, v4, v4 row_ror:4 row_mask:0xf bank_mask:0xf bound_ctrl:1
	ds_read_b128 v[76:79], v88 offset:16384
	v_add_f32_dpp v200, v200, v200 quad_perm:[2,3,0,1] row_mask:0xf bank_mask:0xf bound_ctrl:1
	v_add_f32_dpp v4, v4, v4 row_ror:8 row_mask:0xf bank_mask:0xf bound_ctrl:1
	v_pk_fma_f32 v[0:1], v[4:5], v[32:33], v[8:9] op_sel_hi:[0,1,1]
	v_pk_fma_f32 v[2:3], v[4:5], v[34:35], v[10:11] op_sel_hi:[0,1,1]
	v_pk_mul_f32 v[6:7], v[0:1], v[36:37]
	v_pk_fma_f32 v[6:7], v[2:3], v[38:39], v[6:7]
	v_add_f32_e32 v190, v6, v7
	ds_read2st64_b32 v[18:19], v90 offset0:65 offset1:71
	v_cndmask_b32_e64 v214, v198, v200, s[34:35]
	v_cvt_pk_bf16_f32 v214, v214, v214
	ds_write_b128 v91, v[176:179] offset:24832
	v_lshlrev_b32_e32 v176, 16, v166
	s_waitcnt lgkmcnt(7)
	v_pk_mul_f32 v[4:5], v[0:1], v[48:49] neg_lo:[0,1] neg_hi:[0,1]
	ds_read_b128 v[92:95], v88 offset:17408
	v_pk_fma_f32 v[4:5], v[2:3], v[50:51], v[4:5] neg_lo:[0,1,0] neg_hi:[0,1,0]
	ds_read_b128 v[84:87], v88 offset:17152
	v_pk_mul_f32 v[8:9], v[44:45], v[16:17] op_sel:[0,1] op_sel_hi:[1,1]
	v_add_f32_e32 v4, v4, v5
	ds_read_b128 v[80:83], v88 offset:16896
	v_pk_mul_f32 v[10:11], v[46:47], v[16:17] op_sel:[0,1] op_sel_hi:[1,1]
	v_add_f32_dpp v4, v4, v4 quad_perm:[1,0,3,2] row_mask:0xf bank_mask:0xf bound_ctrl:1
	ds_read_b128 v[96:99], v88 offset:17664
	v_pk_fma_f32 v[8:9], v[0:1], v[40:41], v[8:9]
	v_add_f32_dpp v4, v4, v4 quad_perm:[2,3,0,1] row_mask:0xf bank_mask:0xf bound_ctrl:1
	v_pk_fma_f32 v[10:11], v[2:3], v[42:43], v[10:11]
	s_nop 0
	v_add_f32_dpp v4, v4, v4 row_ror:4 row_mask:0xf bank_mask:0xf bound_ctrl:1
	ds_read_b128 v[100:103], v88 offset:17920
	s_nop 0
	v_add_f32_dpp v4, v4, v4 row_ror:8 row_mask:0xf bank_mask:0xf bound_ctrl:1
	v_pk_fma_f32 v[0:1], v[4:5], v[52:53], v[8:9] op_sel_hi:[0,1,1]
	v_pk_fma_f32 v[2:3], v[4:5], v[54:55], v[10:11] op_sel_hi:[0,1,1]
	v_pk_mul_f32 v[6:7], v[0:1], v[56:57]
	v_pk_fma_f32 v[6:7], v[2:3], v[58:59], v[6:7]
	v_add_f32_e32 v191, v6, v7
	global_store_short v145, v214, s[22:23]
	v_add_u32_e32 v145, s26, v145
	v_and_b32_e32 v177, 0xffff0000, v166
	v_lshlrev_b32_e32 v178, 16, v167
	s_waitcnt lgkmcnt(6)
	v_pk_mul_f32 v[4:5], v[0:1], v[68:69] neg_lo:[0,1] neg_hi:[0,1]
	ds_read_b128 v[28:31], v88 offset:18944
	v_pk_fma_f32 v[4:5], v[2:3], v[70:71], v[4:5] neg_lo:[0,1,0] neg_hi:[0,1,0]
	ds_read_b128 v[24:27], v88 offset:18688
	v_pk_mul_f32 v[8:9], v[64:65], v[18:19] op_sel_hi:[1,0]
	v_add_f32_e32 v4, v4, v5
	ds_read_b128 v[20:23], v88 offset:18432
	v_pk_mul_f32 v[10:11], v[66:67], v[18:19] op_sel_hi:[1,0]
	v_add_f32_dpp v4, v4, v4 quad_perm:[1,0,3,2] row_mask:0xf bank_mask:0xf bound_ctrl:1
	ds_read_b128 v[32:35], v88 offset:19200
	v_pk_fma_f32 v[8:9], v[0:1], v[60:61], v[8:9]
	v_add_f32_dpp v4, v4, v4 quad_perm:[2,3,0,1] row_mask:0xf bank_mask:0xf bound_ctrl:1
	v_pk_fma_f32 v[10:11], v[2:3], v[62:63], v[10:11]
	s_nop 0
	v_add_f32_dpp v4, v4, v4 row_ror:4 row_mask:0xf bank_mask:0xf bound_ctrl:1
	ds_read_b128 v[36:39], v88 offset:19456
	s_nop 0
	v_add_f32_dpp v4, v4, v4 row_ror:8 row_mask:0xf bank_mask:0xf bound_ctrl:1
	v_pk_fma_f32 v[0:1], v[4:5], v[72:73], v[8:9] op_sel_hi:[0,1,1]
	v_pk_fma_f32 v[2:3], v[4:5], v[74:75], v[10:11] op_sel_hi:[0,1,1]
	v_pk_mul_f32 v[6:7], v[0:1], v[76:77]
	v_pk_fma_f32 v[6:7], v[2:3], v[78:79], v[6:7]
	v_add_f32_e32 v192, v6, v7
	ds_read2st64_b32 v[16:17], v90 offset0:77 offset1:83
	v_and_b32_e32 v179, 0xffff0000, v167
	ds_write_b128 v91, v[176:179] offset:25088
	s_waitcnt lgkmcnt(7)
	v_pk_mul_f32 v[4:5], v[0:1], v[92:93] neg_lo:[0,1] neg_hi:[0,1]
	ds_read_b128 v[48:51], v88 offset:20480
	v_pk_fma_f32 v[4:5], v[2:3], v[94:95], v[4:5] neg_lo:[0,1,0] neg_hi:[0,1,0]
	ds_read_b128 v[44:47], v88 offset:20224
	v_pk_mul_f32 v[8:9], v[84:85], v[18:19] op_sel:[0,1] op_sel_hi:[1,1]
	v_add_f32_e32 v4, v4, v5
	ds_read_b128 v[40:43], v88 offset:19968
	v_pk_mul_f32 v[10:11], v[86:87], v[18:19] op_sel:[0,1] op_sel_hi:[1,1]
	v_add_f32_dpp v4, v4, v4 quad_perm:[1,0,3,2] row_mask:0xf bank_mask:0xf bound_ctrl:1
	ds_read_b128 v[52:55], v88 offset:20736
	v_pk_fma_f32 v[8:9], v[0:1], v[80:81], v[8:9]
	v_add_f32_dpp v4, v4, v4 quad_perm:[2,3,0,1] row_mask:0xf bank_mask:0xf bound_ctrl:1
	v_pk_fma_f32 v[10:11], v[2:3], v[82:83], v[10:11]
	s_nop 0
	v_add_f32_dpp v4, v4, v4 row_ror:4 row_mask:0xf bank_mask:0xf bound_ctrl:1
	ds_read_b128 v[56:59], v88 offset:20992
	s_nop 0
	v_add_f32_dpp v4, v4, v4 row_ror:8 row_mask:0xf bank_mask:0xf bound_ctrl:1
	v_pk_fma_f32 v[0:1], v[4:5], v[96:97], v[8:9] op_sel_hi:[0,1,1]
	v_pk_fma_f32 v[2:3], v[4:5], v[98:99], v[10:11] op_sel_hi:[0,1,1]
	v_pk_mul_f32 v[6:7], v[0:1], v[100:101]
	v_pk_fma_f32 v[6:7], v[2:3], v[102:103], v[6:7]
	v_add_f32_e32 v193, v6, v7
	v_lshlrev_b32_e32 v176, 16, v168
	v_and_b32_e32 v177, 0xffff0000, v168
	s_waitcnt lgkmcnt(6)
	v_pk_mul_f32 v[4:5], v[0:1], v[28:29] neg_lo:[0,1] neg_hi:[0,1]
	ds_read_b128 v[68:71], v88 offset:22016
	v_pk_fma_f32 v[4:5], v[2:3], v[30:31], v[4:5] neg_lo:[0,1,0] neg_hi:[0,1,0]
	ds_read_b128 v[64:67], v88 offset:21760
	v_pk_mul_f32 v[8:9], v[24:25], v[16:17] op_sel_hi:[1,0]
	v_add_f32_e32 v4, v4, v5
	ds_read_b128 v[60:63], v88 offset:21504
	v_pk_mul_f32 v[10:11], v[26:27], v[16:17] op_sel_hi:[1,0]
	v_add_f32_dpp v4, v4, v4 quad_perm:[1,0,3,2] row_mask:0xf bank_mask:0xf bound_ctrl:1
	ds_read_b128 v[72:75], v88 offset:22272
	v_pk_fma_f32 v[8:9], v[0:1], v[20:21], v[8:9]
	v_add_f32_dpp v4, v4, v4 quad_perm:[2,3,0,1] row_mask:0xf bank_mask:0xf bound_ctrl:1
	v_pk_fma_f32 v[10:11], v[2:3], v[22:23], v[10:11]
	s_nop 0
	v_add_f32_dpp v4, v4, v4 row_ror:4 row_mask:0xf bank_mask:0xf bound_ctrl:1
	ds_read_b128 v[76:79], v88 offset:22528
	s_nop 0
	v_add_f32_dpp v4, v4, v4 row_ror:8 row_mask:0xf bank_mask:0xf bound_ctrl:1
	v_pk_fma_f32 v[0:1], v[4:5], v[32:33], v[8:9] op_sel_hi:[0,1,1]
	v_pk_fma_f32 v[2:3], v[4:5], v[34:35], v[10:11] op_sel_hi:[0,1,1]
	v_pk_mul_f32 v[6:7], v[0:1], v[36:37]
	v_pk_fma_f32 v[6:7], v[2:3], v[38:39], v[6:7]
	v_add_f32_e32 v194, v6, v7
	ds_read2st64_b32 v[18:19], v90 offset0:89 offset1:95
	v_lshlrev_b32_e32 v178, 16, v169
	v_and_b32_e32 v179, 0xffff0000, v169
	ds_write_b128 v91, v[176:179] offset:25344
	s_waitcnt lgkmcnt(7)
	v_pk_mul_f32 v[4:5], v[0:1], v[48:49] neg_lo:[0,1] neg_hi:[0,1]
	ds_read_b128 v[92:95], v88 offset:23552
	v_pk_fma_f32 v[4:5], v[2:3], v[50:51], v[4:5] neg_lo:[0,1,0] neg_hi:[0,1,0]
	ds_read_b128 v[84:87], v88 offset:23296
	v_pk_mul_f32 v[8:9], v[44:45], v[16:17] op_sel:[0,1] op_sel_hi:[1,1]
	v_add_f32_e32 v4, v4, v5
	ds_read_b128 v[80:83], v88 offset:23040
	v_pk_mul_f32 v[10:11], v[46:47], v[16:17] op_sel:[0,1] op_sel_hi:[1,1]
	v_add_f32_dpp v4, v4, v4 quad_perm:[1,0,3,2] row_mask:0xf bank_mask:0xf bound_ctrl:1
	ds_read_b128 v[96:99], v88 offset:23808
	v_pk_fma_f32 v[8:9], v[0:1], v[40:41], v[8:9]
	v_add_f32_dpp v4, v4, v4 quad_perm:[2,3,0,1] row_mask:0xf bank_mask:0xf bound_ctrl:1
	v_pk_fma_f32 v[10:11], v[2:3], v[42:43], v[10:11]
	s_nop 0
	v_add_f32_dpp v4, v4, v4 row_ror:4 row_mask:0xf bank_mask:0xf bound_ctrl:1
	ds_read_b128 v[100:103], v88 offset:24064
	s_nop 0
	v_add_f32_dpp v4, v4, v4 row_ror:8 row_mask:0xf bank_mask:0xf bound_ctrl:1
	v_pk_fma_f32 v[0:1], v[4:5], v[52:53], v[8:9] op_sel_hi:[0,1,1]
	v_pk_fma_f32 v[2:3], v[4:5], v[54:55], v[10:11] op_sel_hi:[0,1,1]
	v_pk_mul_f32 v[6:7], v[0:1], v[56:57]
	v_pk_fma_f32 v[6:7], v[2:3], v[58:59], v[6:7]
	v_add_f32_e32 v195, v6, v7
	s_waitcnt lgkmcnt(0)
	s_barrier
	v_pk_mul_f32 v[4:5], v[0:1], v[68:69] neg_lo:[0,1] neg_hi:[0,1]
	ds_read_b128 v[28:31], v88 offset:25088
	v_pk_fma_f32 v[4:5], v[2:3], v[70:71], v[4:5] neg_lo:[0,1,0] neg_hi:[0,1,0]
	ds_read_b128 v[24:27], v88 offset:24832
	v_pk_mul_f32 v[8:9], v[64:65], v[18:19] op_sel_hi:[1,0]
	v_add_f32_e32 v4, v4, v5
	ds_read_b128 v[20:23], v88 offset:24576
	v_pk_mul_f32 v[10:11], v[66:67], v[18:19] op_sel_hi:[1,0]
	v_add_f32_dpp v4, v4, v4 quad_perm:[1,0,3,2] row_mask:0xf bank_mask:0xf bound_ctrl:1
	ds_read_b128 v[32:35], v88 offset:25344
	v_pk_fma_f32 v[8:9], v[0:1], v[60:61], v[8:9]
	v_add_f32_dpp v4, v4, v4 quad_perm:[2,3,0,1] row_mask:0xf bank_mask:0xf bound_ctrl:1
	v_pk_fma_f32 v[10:11], v[2:3], v[62:63], v[10:11]
	s_nop 0
	v_add_f32_dpp v4, v4, v4 row_ror:4 row_mask:0xf bank_mask:0xf bound_ctrl:1
	ds_read_b128 v[36:39], v88 offset:25600
	s_nop 0
	v_add_f32_dpp v4, v4, v4 row_ror:8 row_mask:0xf bank_mask:0xf bound_ctrl:1
	v_pk_fma_f32 v[0:1], v[4:5], v[72:73], v[8:9] op_sel_hi:[0,1,1]
	v_pk_fma_f32 v[2:3], v[4:5], v[74:75], v[10:11] op_sel_hi:[0,1,1]
	v_pk_mul_f32 v[6:7], v[0:1], v[76:77]
	v_pk_fma_f32 v[6:7], v[2:3], v[78:79], v[6:7]
	v_add_f32_e32 v196, v6, v7
	ds_read2st64_b32 v[16:17], v90 offset0:101 offset1:107
	s_waitcnt lgkmcnt(6)
	v_pk_mul_f32 v[4:5], v[0:1], v[92:93] neg_lo:[0,1] neg_hi:[0,1]
	ds_read_b128 v[48:51], v88 offset:26624
	v_pk_fma_f32 v[4:5], v[2:3], v[94:95], v[4:5] neg_lo:[0,1,0] neg_hi:[0,1,0]
	ds_read_b128 v[44:47], v88 offset:26368
	v_pk_mul_f32 v[8:9], v[84:85], v[18:19] op_sel:[0,1] op_sel_hi:[1,1]
	v_add_f32_e32 v4, v4, v5
	ds_read_b128 v[40:43], v88 offset:26112
	v_pk_mul_f32 v[10:11], v[86:87], v[18:19] op_sel:[0,1] op_sel_hi:[1,1]
	v_add_f32_dpp v4, v4, v4 quad_perm:[1,0,3,2] row_mask:0xf bank_mask:0xf bound_ctrl:1
	ds_read_b128 v[52:55], v88 offset:26880
	v_pk_fma_f32 v[8:9], v[0:1], v[80:81], v[8:9]
	v_add_f32_dpp v4, v4, v4 quad_perm:[2,3,0,1] row_mask:0xf bank_mask:0xf bound_ctrl:1
	v_pk_fma_f32 v[10:11], v[2:3], v[82:83], v[10:11]
	s_nop 0
	v_add_f32_dpp v4, v4, v4 row_ror:4 row_mask:0xf bank_mask:0xf bound_ctrl:1
	ds_read_b128 v[56:59], v88 offset:27136
	s_nop 0
	v_add_f32_dpp v4, v4, v4 row_ror:8 row_mask:0xf bank_mask:0xf bound_ctrl:1
	v_pk_fma_f32 v[0:1], v[4:5], v[96:97], v[8:9] op_sel_hi:[0,1,1]
	v_pk_fma_f32 v[2:3], v[4:5], v[98:99], v[10:11] op_sel_hi:[0,1,1]
	v_pk_mul_f32 v[6:7], v[0:1], v[100:101]
	v_pk_fma_f32 v[6:7], v[2:3], v[102:103], v[6:7]
	v_add_f32_e32 v197, v6, v7
	s_waitcnt lgkmcnt(5)
	v_pk_mul_f32 v[4:5], v[0:1], v[28:29] neg_lo:[0,1] neg_hi:[0,1]
	ds_read_b128 v[68:71], v88 offset:28160
	v_pk_fma_f32 v[4:5], v[2:3], v[30:31], v[4:5] neg_lo:[0,1,0] neg_hi:[0,1,0]
	ds_read_b128 v[64:67], v88 offset:27904
	v_pk_mul_f32 v[8:9], v[24:25], v[16:17] op_sel_hi:[1,0]
	v_add_f32_e32 v4, v4, v5
	ds_read_b128 v[60:63], v88 offset:27648
	v_pk_mul_f32 v[10:11], v[26:27], v[16:17] op_sel_hi:[1,0]
	v_add_f32_dpp v4, v4, v4 quad_perm:[1,0,3,2] row_mask:0xf bank_mask:0xf bound_ctrl:1
	ds_read_b128 v[72:75], v88 offset:28416
	v_pk_fma_f32 v[8:9], v[0:1], v[20:21], v[8:9]
	v_add_f32_dpp v4, v4, v4 quad_perm:[2,3,0,1] row_mask:0xf bank_mask:0xf bound_ctrl:1
	v_pk_fma_f32 v[10:11], v[2:3], v[22:23], v[10:11]
	v_add_f32_dpp v182, v182, v182 row_ror:8 row_mask:0xf bank_mask:0x3 bound_ctrl:1
	v_add_f32_dpp v4, v4, v4 row_ror:4 row_mask:0xf bank_mask:0xf bound_ctrl:1
	ds_read_b128 v[76:79], v88 offset:28672
	v_add_f32_dpp v182, v190, v190 row_ror:8 row_mask:0xf bank_mask:0xc bound_ctrl:1
	v_add_f32_dpp v4, v4, v4 row_ror:8 row_mask:0xf bank_mask:0xf bound_ctrl:1
	v_pk_fma_f32 v[0:1], v[4:5], v[32:33], v[8:9] op_sel_hi:[0,1,1]
	v_pk_fma_f32 v[2:3], v[4:5], v[34:35], v[10:11] op_sel_hi:[0,1,1]
	v_pk_mul_f32 v[6:7], v[0:1], v[36:37]
	v_pk_fma_f32 v[6:7], v[2:3], v[38:39], v[6:7]
	v_add_f32_e32 v198, v6, v7
	ds_read2st64_b32 v[18:19], v90 offset0:113 offset1:119
	s_cmp_lt_u32 s28, 15
	s_cbranch_scc0 .Lls0_skip3
	global_load_dwordx4 v[128:131], v174, s[12:13] nt
	global_load_dwordx2 v[164:165], v175, s[14:15] nt
	global_load_dwordx2 v[166:167], v175, s[16:17] nt
	global_load_dwordx2 v[168:169], v175, s[18:19] nt
	global_load_dwordx4 v[132:135], v180, s[20:21]
	global_load_dword v173, v181, s[20:21]
	v_add_u32_e32 v174, s25, v174
	v_add_u32_e32 v175, s26, v175
	v_add_u32_e32 v180, s27, v180
	v_add_u32_e32 v181, s27, v181

.LBB0_1950:
	s_and_b64 vcc, exec, s[0:1]
	s_cbranch_vccz .LBB0_1958
	s_add_i32 s0, s24, 0xffa0
	s_and_b32 s1, s0, 0xffff
	s_mul_i32 s1, s1, 0xaaab
	s_lshr_b32 s22, s1, 19
	s_mul_i32 s1, s22, 12
	s_and_b32 s25, s24, 1
	s_sub_i32 s2, s0, s1
	s_mul_i32 s0, s25, 0x3c0000
	s_bfe_u32 s23, s2, 0xf0001
	s_lshl_b32 s26, s22, 8
	s_lshl_b32 s1, s0, 2
	s_add_u32 s4, s54, s1
	s_addc_u32 s5, s55, 0
	s_lshl_b32 s3, s0, 1
	s_add_u32 s6, s62, s3
	s_addc_u32 s7, s63, 0
	s_add_u32 s0, s64, s3
	s_addc_u32 s1, s65, 0
	s_lshl_b32 s2, s2, 5
	s_add_u32 s3, s70, s3
	s_addc_u32 s9, s71, 0
	s_and_b32 s10, s2, 0xffc0
	s_lshl_b32 s58, s10, 1
	s_add_u32 s8, s3, s58
	s_waitcnt vmcnt(6)
	v_mov_b32_e32 v24, v137
	s_addc_u32 s9, s9, 0
	s_cmp_eq_u32 s25, 0
	s_waitcnt vmcnt(1)
	v_ashrrev_i32_e32 v33, 4, v24
	v_lshlrev_b32_e32 v0, 2, v24
	v_and_b32_e32 v6, 60, v0
	v_sub_u32_e32 v0, 0xff, v33
	s_cselect_b64 s[2:3], -1, 0
	v_cndmask_b32_e64 v0, v0, v33, s[2:3]
	v_add_u32_e32 v7, s26, v0
	v_mul_lo_u32 v88, v7, s50
	v_lshlrev_b64 v[12:13], 1, v[88:89]
	v_lshl_add_u64 v[4:5], s[6:7], 0, v[12:13]
	v_lshl_add_u64 v[0:1], v[88:89], 2, s[4:5]
	v_lshl_add_u64 v[4:5], v[4:5], 0, s[58:59]
	v_lshlrev_b32_e32 v88, 1, v6
	v_lshl_add_u64 v[14:15], v[4:5], 0, v[88:89]
	v_mul_lo_u32 v4, v7, s51
	v_mov_b32_e32 v5, v89
	s_lshl_b32 s20, s10, 2
	s_mov_b32 s21, s59
	v_lshl_add_u64 v[4:5], v[4:5], 2, s[52:53]
	v_lshl_add_u64 v[0:1], v[0:1], 0, s[20:21]
	v_lshlrev_b32_e32 v20, 2, v6
	v_mov_b32_e32 v21, v89
	v_lshl_add_u64 v[4:5], v[4:5], 0, s[20:21]
	v_lshl_add_u64 v[0:1], v[0:1], 0, v[20:21]
	v_lshl_add_u64 v[8:9], v[4:5], 0, v[20:21]
	s_barrier
	global_load_dwordx4 v[0:3], v[0:1], off nt
	s_nop 0
	global_load_dwordx4 v[4:7], v[8:9], off
	s_nop 0
	global_load_dwordx4 v[8:11], v[8:9], off offset:3072
	s_nop 0
	global_load_dwordx2 v[30:31], v[14:15], off nt
	v_lshl_add_u64 v[14:15], s[74:75], 0, v[12:13]
	v_lshl_add_u64 v[14:15], v[14:15], 0, s[58:59]
	v_lshl_add_u64 v[12:13], s[0:1], 0, v[12:13]
	v_lshl_add_u64 v[14:15], v[14:15], 0, v[88:89]
	v_lshl_add_u64 v[12:13], v[12:13], 0, s[58:59]
	global_load_dwordx2 v[34:35], v[14:15], off nt
	v_lshl_add_u64 v[12:13], v[12:13], 0, v[88:89]
	global_load_dwordx2 v[38:39], v[12:13], off nt
	s_add_u32 s4, s4, s20
	s_addc_u32 s5, s5, 0
	v_lshl_add_u64 v[40:41], s[4:5], 0, v[20:21]
	s_add_u32 s4, s6, s58
	s_addc_u32 s5, s7, 0
	v_lshl_add_u64 v[42:43], s[4:5], 0, v[88:89]
	s_add_u32 s4, s74, s58
	s_addc_u32 s5, s75, 0
	s_add_u32 s0, s0, s58
	v_add_u32_e32 v32, 0, v20
	s_addc_u32 s1, s1, 0
	v_ashrrev_i32_e32 v116, 2, v24
	v_mad_u64_u32 v[22:23], s[10:11], v33, s45, v[32:33]
	v_lshl_add_u64 v[46:47], s[0:1], 0, v[88:89]
	s_add_u32 s0, s52, s20
	v_and_b32_e32 v28, -2, v116
	s_addc_u32 s1, s53, 0
	v_and_b32_e32 v118, 7, v24
	v_ashrrev_i32_e32 v29, 31, v28
	v_lshl_add_u64 v[48:49], s[0:1], 0, v[20:21]
	s_movk_i32 s0, 0xf7
	s_mov_b32 s21, 0
	s_mov_b32 s27, 16
	v_lshlrev_b32_e32 v117, 3, v118
	v_lshl_add_u64 v[36:37], v[28:29], 1, s[8:9]
	v_lshl_add_u64 v[44:45], s[4:5], 0, v[88:89]
	v_cmp_eq_u32_e64 s[4:5], 0, v118
	v_cmp_eq_u32_e64 s[6:7], 1, v118
	v_cmp_eq_u32_e64 s[8:9], 2, v118
	v_cmp_eq_u32_e64 s[10:11], 3, v118
	v_cmp_eq_u32_e64 s[12:13], 4, v118
	v_cmp_eq_u32_e64 s[14:15], 5, v118
	v_cmp_eq_u32_e64 s[16:17], 6, v118
	v_cmp_eq_u32_e64 s[18:19], 7, v118
	v_bitop3_b32 v29, v24, s0, 7 bitop3:0x6c
	v_sub_u32_e32 v119, 0xef, v33
	s_waitcnt vmcnt(5)
	ds_write_b128 v22, v[0:3]
	s_waitcnt vmcnt(4)
	ds_write_b128 v22, v[4:7] offset:1024
	s_waitcnt vmcnt(3)
	ds_write_b128 v22, v[8:11] offset:1280
	s_waitcnt vmcnt(2)
	v_lshlrev_b32_e32 v12, 16, v30
	v_and_b32_e32 v13, 0xffff0000, v30
	v_lshlrev_b32_e32 v14, 16, v31
	v_and_b32_e32 v15, 0xffff0000, v31
	ds_write_b128 v22, v[12:15] offset:256
	s_waitcnt vmcnt(1)
	v_lshlrev_b32_e32 v26, 16, v35
	v_lshlrev_b32_e32 v23, 16, v34
	v_and_b32_e32 v25, 0xffff0000, v34
	v_and_b32_e32 v27, 0xffff0000, v35
	s_waitcnt vmcnt(0)
	v_lshlrev_b32_e32 v16, 16, v38
	v_and_b32_e32 v17, 0xffff0000, v38
	v_lshlrev_b32_e32 v18, 16, v39
	v_and_b32_e32 v19, 0xffff0000, v39
	v_xor_b32_e32 v14, 0x80000000, v26
	v_xor_b32_e32 v13, 0x80000000, v25
	v_xor_b32_e32 v12, 0x80000000, v23
	v_xor_b32_e32 v15, 0x80000000, v27
	ds_write_b128 v22, v[16:19] offset:768
	ds_write_b128 v22, v[12:15] offset:512
	v_mov_b32_e32 v14, 0
	v_mov_b32_e32 v15, v14
	v_mov_b32_e32 v12, v14
	v_mov_b32_e32 v13, v14
	v_mov_b32_e32 v18, v14
	v_mov_b32_e32 v19, v14
	v_mov_b32_e32 v16, v14
	v_mov_b32_e32 v17, v14
	v_mov_b32_e32 v22, v14
	v_mov_b32_e32 v23, v14
	v_mov_b32_e32 v20, v14
	v_mov_b32_e32 v21, v14
	v_mov_b32_e32 v26, v14
	v_mov_b32_e32 v27, v14
	v_mov_b32_e32 v24, v14
	v_mov_b32_e32 v25, v14
	s_waitcnt lgkmcnt(0)
	s_barrier
	s_branch .LBB0_1953

.LBB0_1953:
	s_cmpk_lg_i32 s27, 0x100
	s_cselect_b64 s[0:1], -1, 0
	s_cmpk_eq_i32 s27, 0x100
	s_cbranch_scc1 .LBB0_1955
	s_waitcnt vmcnt(7)
	v_add_u32_e32 v0, s27, v33
	v_cndmask_b32_e64 v0, v119, v0, s[2:3]
	s_waitcnt vmcnt(2)
	v_add_u32_e32 v8, s26, v0
	v_mul_lo_u32 v88, v8, s50
	v_lshlrev_b64 v[4:5], 1, v[88:89]
	v_lshl_add_u64 v[0:1], v[88:89], 2, v[40:41]
	v_lshl_add_u64 v[6:7], v[42:43], 0, v[4:5]
	v_mul_lo_u32 v88, v8, s51
	global_load_dwordx4 v[0:3], v[0:1], off nt
	s_nop 0
	global_load_dwordx2 v[30:31], v[6:7], off nt
	v_lshl_add_u64 v[6:7], v[44:45], 0, v[4:5]
	v_lshl_add_u64 v[4:5], v[46:47], 0, v[4:5]
	v_lshl_add_u64 v[8:9], v[88:89], 2, v[48:49]
	global_load_dwordx2 v[34:35], v[6:7], off nt
	global_load_dwordx2 v[38:39], v[4:5], off nt
	s_nop 0
	global_load_dwordx4 v[4:7], v[8:9], off
	s_nop 0
	global_load_dwordx4 v[8:11], v[8:9], off offset:3072

.LBB0_1959:
	s_waitcnt vmcnt(0) lgkmcnt(0)
	v_readlane_b32 s0, v242, 42
	v_readlane_b32 s1, v242, 43
	v_readlane_b32 s4, v242, 3
	v_readlane_b32 s5, v242, 4
	s_lshr_b32 s6, s24, 2
	s_and_b32 s7, s24, 3
	s_cmp_gt_u32 s6, 11
	s_cselect_b32 s8, 1, 0
	s_mul_i32 s9, s8, 12
	s_sub_i32 s9, s6, s9
	s_sub_u32 s0, s0, 0x118
	s_subb_u32 s1, s1, 0
	s_load_dwordx2 s[2:3], s[0:1], 0x30
	s_lshr_b32 s10, s9, 1
	s_and_b32 s11, s9, 1
	s_lshl_b32 s29, s8, 1
	s_add_i32 s29, s29, 1
	s_lshl_b32 s29, s29, 1
	s_add_i32 s29, s29, s11
	s_mul_i32 s29, s29, 6
	s_add_i32 s29, s29, s10
	s_lshl_b32 s29, s29, 14
	v_and_b32_e32 v20, 15, v137
	v_lshrrev_b32_e32 v21, 4, v137
	v_lshlrev_b32_e32 v22, 4, v137
	s_lshl_b32 s38, s7, 12
	v_add_u32_e32 v22, s38, v22
	s_waitcnt lgkmcnt(0)
	s_add_u32 s2, s2, s29
	s_addc_u32 s3, s3, 0
	global_load_dwordx4 v[0:3], v22, s[2:3]
	s_mul_i32 s38, s11, 0xf00000
	s_mul_i32 s39, s11, 0x780000
	s_add_u32 s29, s38, 0x9278100
	s_add_u32 s12, s4, s29
	s_addc_u32 s13, s5, 0
	s_add_u32 s29, s39, 0xb078100
	s_add_u32 s14, s4, s29
	s_addc_u32 s15, s5, 0
	s_add_u32 s29, s39, 0xbf78100
	s_add_u32 s18, s4, s29
	s_addc_u32 s19, s5, 0
	s_add_u32 s29, s39, 0xddc8100
	s_add_u32 s22, s4, s29
	s_addc_u32 s23, s5, 0
	s_add_u32 s16, s4, 0xce78100
	s_addc_u32 s17, s5, 0
	s_add_u32 s20, s4, 0x5b78100
	s_addc_u32 s21, s5, 0
	s_lshl_b32 s38, s11, 1
	s_sub_i32 s38, 1, s38
	s_mul_i32 s25, s38, 24576
	s_mul_i32 s26, s38, 12288
	s_mul_i32 s27, s38, 0x16000
	s_lshl_b32 s39, s8, 10
	s_addk_i32 s39, 0x2000
	s_mul_i32 s44, s11, 1023
	s_add_i32 s39, s39, s44
	v_mul_i32_i24_e32 v23, s38, v21
	v_mul_i32_i24_e32 v24, s38, v20
	v_add_u32_e32 v23, s39, v23
	v_add_u32_e32 v24, s39, v24
	s_lshl_b32 s38, s10, 8
	s_lshl_b32 s39, s10, 7
	s_movk_i32 s44, 0x600
	v_lshlrev_b32_e32 v25, 4, v20
	v_mul_lo_u32 v174, v23, s44
	v_add3_u32 v174, v174, s38, v25
	s_movk_i32 s44, 0x300
	v_lshlrev_b32_e32 v26, 3, v20
	v_mul_lo_u32 v175, v23, s44
	v_add3_u32 v175, v175, s39, v26
	v_mul_lo_u32 v145, v24, s44
	s_lshl_b32 s44, s7, 5
	s_add_i32 s44, s44, s39
	v_lshlrev_b32_e32 v27, 1, v21
	v_add3_u32 v145, v145, s44, v27
	s_movk_i32 s44, 0x1600
	v_mul_lo_u32 v180, v23, s44
	v_lshlrev_b32_e32 v28, 2, v20
	s_lshl_b32 s44, s7, 6
	s_add_i32 s44, s44, s38
	s_addk_i32 s44, 0xc00
	v_add3_u32 v181, v180, s44, v28
	v_add3_u32 v180, v180, s38, v25
	v_mov_b32_e32 v88, v25
	v_lshlrev_b32_e32 v90, 4, v21
	v_mul_u32_u24_e32 v91, 0x600, v21
	v_add_u32_e32 v91, v91, v25
	v_and_b32_e32 v29, 1, v20
	v_and_b32_e32 v30, 2, v20
	v_cmp_ne_u32_e64 s[30:31], 0, v29
	v_cmp_ne_u32_e64 s[34:35], 0, v30
	v_and_b32_e32 v29, 3, v20
	v_cmp_eq_u32_e64 s[36:37], 3, v29
	s_mov_b32 s28, 0
	s_setprio 3
	global_load_dwordx4 v[104:107], v174, s[12:13] nt
	global_load_dwordx2 v[146:147], v175, s[14:15] nt
	global_load_dwordx2 v[148:149], v175, s[16:17] nt
	global_load_dwordx2 v[150:151], v175, s[18:19] nt
	global_load_dwordx4 v[108:111], v180, s[20:21]
	global_load_dword v170, v181, s[20:21]
	v_add_u32_e32 v174, s25, v174
	v_add_u32_e32 v175, s26, v175
	v_add_u32_e32 v180, s27, v180
	v_add_u32_e32 v181, s27, v181
	global_load_dwordx4 v[112:115], v174, s[12:13] nt
	global_load_dwordx2 v[152:153], v175, s[14:15] nt
	global_load_dwordx2 v[154:155], v175, s[16:17] nt
	global_load_dwordx2 v[156:157], v175, s[18:19] nt
	global_load_dwordx4 v[116:119], v180, s[20:21]
	global_load_dword v171, v181, s[20:21]
	v_add_u32_e32 v174, s25, v174
	v_add_u32_e32 v175, s26, v175
	v_add_u32_e32 v180, s27, v180
	v_add_u32_e32 v181, s27, v181
	global_load_dwordx4 v[120:123], v174, s[12:13] nt
	global_load_dwordx2 v[158:159], v175, s[14:15] nt
	global_load_dwordx2 v[160:161], v175, s[16:17] nt
	global_load_dwordx2 v[162:163], v175, s[18:19] nt
	global_load_dwordx4 v[124:127], v180, s[20:21]
	global_load_dword v172, v181, s[20:21]
	v_add_u32_e32 v174, s25, v174
	v_add_u32_e32 v175, s26, v175
	v_add_u32_e32 v180, s27, v180
	v_add_u32_e32 v181, s27, v181
	global_load_dwordx4 v[128:131], v174, s[12:13] nt
	global_load_dwordx2 v[164:165], v175, s[14:15] nt
	global_load_dwordx2 v[166:167], v175, s[16:17] nt
	global_load_dwordx2 v[168:169], v175, s[18:19] nt
	global_load_dwordx4 v[132:135], v180, s[20:21]
	global_load_dword v173, v181, s[20:21]
	v_add_u32_e32 v174, s25, v174
	v_add_u32_e32 v175, s26, v175
	v_add_u32_e32 v180, s27, v180
	v_add_u32_e32 v181, s27, v181
	s_waitcnt vmcnt(18)
	ds_write_b128 v91, v[104:107] offset:0
	ds_write_b128 v91, v[108:111] offset:1024
	ds_write_b32 v91, v170 offset:1280
	v_lshlrev_b32_e32 v176, 16, v146
	v_and_b32_e32 v177, 0xffff0000, v146
	v_lshlrev_b32_e32 v178, 16, v147
	v_and_b32_e32 v179, 0xffff0000, v147
	ds_write_b128 v91, v[176:179] offset:256
	v_lshlrev_b32_e32 v176, 16, v148
	v_and_b32_e32 v177, 0xffff0000, v148
	v_lshlrev_b32_e32 v178, 16, v149
	v_and_b32_e32 v179, 0xffff0000, v149
	ds_write_b128 v91, v[176:179] offset:512
	v_lshlrev_b32_e32 v176, 16, v150
	v_and_b32_e32 v177, 0xffff0000, v150
	v_lshlrev_b32_e32 v178, 16, v151
	v_and_b32_e32 v179, 0xffff0000, v151
	ds_write_b128 v91, v[176:179] offset:768
	s_waitcnt lgkmcnt(0)
	s_barrier
	ds_read_b128 v[28:31], v88 offset:512
	ds_read_b128 v[24:27], v88 offset:256
	ds_read_b128 v[20:23], v88 offset:0
	ds_read_b128 v[32:35], v88 offset:768
	ds_read_b128 v[36:39], v88 offset:1024
	ds_read2st64_b32 v[16:17], v90 offset0:5 offset1:11
	ds_read_b128 v[48:51], v88 offset:2048
	ds_read_b128 v[44:47], v88 offset:1792
	ds_read_b128 v[40:43], v88 offset:1536
	ds_read_b128 v[52:55], v88 offset:2304
	ds_read_b128 v[56:59], v88 offset:2560
